# software-pipelined K-loop (1 barrier per K-tile, staggered DMA slots) in the four FFN_IN GEMMs
# baseline (speedup 1.0000x reference)
.LBB0_146:
	s_waitcnt lgkmcnt(0)
	s_add_u32 s12, s4, 0xa400000
	s_addc_u32 s13, s5, 0
	s_lshl_b32 s4, s14, 5
	s_mov_b64 s[14:15], 0x80
	s_and_b32 s26, s4, 0x60
	s_add_i32 m0, s57, 0x18000
	v_lshl_add_u64 v[8:9], v[8:9], 0, s[14:15]
	s_lshl_b32 s25, s24, 13
	s_lshl_b32 s27, s26, 7
	s_waitcnt vmcnt(2)
	global_load_lds_dwordx4 v[8:9], off
	v_lshl_add_u64 v[6:7], v[6:7], 0, s[14:15]
	s_add_i32 m0, s57, 0x1a000
	s_add_i32 s62, s57, 0x8000
	s_add_i32 s63, s57, 0xa000
	global_load_lds_dwordx4 v[6:7], off
	v_lshl_add_u64 v[2:3], v[2:3], 0, s[14:15]
	s_mov_b32 m0, s62
	s_add_u32 s4, s50, 0x40080
	global_load_lds_dwordx4 v[2:3], off
	v_lshl_add_u64 v[2:3], v[4:5], 0, s[14:15]
	s_mov_b32 m0, s63
	s_addc_u32 s5, s51, 0
	global_load_lds_dwordx4 v[2:3], off
	s_add_i32 m0, s57, 0x1c000
	v_lshl_add_u64 v[2:3], s[4:5], 0, v[134:135]
	global_load_lds_dwordx4 v[2:3], off
	v_lshl_add_u64 v[2:3], s[4:5], 0, v[130:131]
	s_add_i32 m0, s57, 0x1e000
	s_cmpk_lt_u32 s17, 0x100
	global_load_lds_dwordx4 v[2:3], off
	v_lshrrev_b32_e32 v3, 1, v10
	v_and_b32_e32 v3, 24, v3
	v_and_b32_e32 v2, 15, v10
	v_lshlrev_b32_e32 v4, 1, v3
	v_lshl_or_b32 v150, s24, 6, v2
	v_lshl_or_b32 v2, v2, 6, v4
	v_lshlrev_b32_e32 v4, 2, v10
	v_and_b32_e32 v4, 32, v4
	v_bitop3_b32 v5, v2, s25, v4 bitop3:0xde
	v_bitop3_b32 v151, v2, s27, v4 bitop3:0xde
	v_or_b32_e32 v2, s26, v3
	v_lshlrev_b32_e32 v3, 14, v15
	v_and_b32_e32 v3, 0xffff8000, v3
	v_lshl_add_u32 v3, v14, 11, v3
	v_and_b32_e32 v4, 1, v15
	v_lshl_or_b32 v3, v4, 6, v3
	v_lshl_add_u32 v140, v16, 1, v3
	v_lshlrev_b32_e32 v3, 14, v11
	v_and_b32_e32 v3, 0xffff8000, v3
	s_waitcnt vmcnt(6)
	v_lshl_add_u32 v3, v12, 11, v3
	v_and_b32_e32 v4, 1, v11
	s_sext_i32_i16 s47, s16
	s_cselect_b64 s[16:17], -1, 0
	v_lshl_or_b32 v3, v4, 6, v3
	s_add_i32 s66, 0, 0x10000
	s_add_i32 s67, 0, 0x14000
	v_or_b32_e32 v152, 16, v150
	v_or_b32_e32 v153, 32, v150
	v_or_b32_e32 v154, 48, v150
	s_ashr_i32 s64, s38, 31
	s_mov_b32 s65, s38
	v_mov_b32_e32 v141, v139
	v_lshl_add_u32 v142, v13, 1, v3
	v_mov_b32_e32 v143, v139
	v_mov_b64_e32 v[144:145], 0xb00
	v_mov_b64_e32 v[146:147], 0xaff
	v_add_u32_e32 v155, s66, v151
	v_add_u32_e32 v156, s67, v151
	v_add_u32_e32 v157, 0, v5
	v_mov_b32_e32 v158, 0x358637bd
	s_movk_i32 s68, 0x1600
	v_lshlrev_b32_e32 v138, 1, v2
	s_add_u32 s98, s48, 0x40080
	s_addc_u32 s99, s49, 0
	v_lshl_add_u64 v[148:149], s[98:99], 0, v[140:141]
	s_add_i32 m0, s57, 0xc000
	s_nop 0
	global_load_lds_dwordx4 v[148:149], off
	v_lshl_add_u64 v[148:149], s[98:99], 0, v[142:143]
	s_add_i32 m0, s57, 0xe000
	s_nop 0
	global_load_lds_dwordx4 v[148:149], off
	s_waitcnt vmcnt(0)
	s_barrier
	s_branch .LBB0_149

.LBB0_151:
	s_ashr_i32 s27, s26, 31
	s_lshl_b64 s[42:43], s[26:27], 19
	s_add_u32 s42, s3, s42
	s_addc_u32 s43, s23, s43
	s_and_b64 s[44:45], s[4:5], exec
	s_cselect_b32 s27, s43, s49
	s_cselect_b32 s69, s42, s48
	s_ashr_i32 s25, s24, 31
	s_lshl_b64 s[44:45], s[24:25], 19
	s_add_u32 s44, s29, s44
	s_addc_u32 s45, s31, s45
	s_and_b64 s[52:53], s[4:5], exec
	s_cselect_b32 s25, s45, s51
	s_cselect_b32 s70, s44, s50
	s_add_u32 s48, s48, 0x40080
	s_addc_u32 s49, s49, 0
	s_add_u32 s71, s50, 0x100
	v_mov_b32_e32 v2, 0
	s_addc_u32 s72, s51, 0
	s_mov_b32 s73, -2
	v_mov_b32_e32 v3, v2
	v_mov_b32_e32 v4, v2
	v_mov_b32_e32 v5, v2
	v_mov_b32_e32 v14, v2
	v_mov_b32_e32 v15, v2
	v_mov_b32_e32 v16, v2
	v_mov_b32_e32 v17, v2
	v_mov_b32_e32 v22, v2
	v_mov_b32_e32 v23, v2
	v_mov_b32_e32 v24, v2
	v_mov_b32_e32 v25, v2
	v_mov_b32_e32 v30, v2
	v_mov_b32_e32 v31, v2
	v_mov_b32_e32 v32, v2
	v_mov_b32_e32 v33, v2
	v_mov_b32_e32 v38, v2
	v_mov_b32_e32 v39, v2
	v_mov_b32_e32 v40, v2
	v_mov_b32_e32 v41, v2
	v_mov_b32_e32 v46, v2
	v_mov_b32_e32 v47, v2
	v_mov_b32_e32 v48, v2
	v_mov_b32_e32 v49, v2
	v_mov_b32_e32 v54, v2
	v_mov_b32_e32 v55, v2
	v_mov_b32_e32 v56, v2
	v_mov_b32_e32 v57, v2
	v_mov_b32_e32 v62, v2
	v_mov_b32_e32 v63, v2
	v_mov_b32_e32 v64, v2
	v_mov_b32_e32 v65, v2
	v_mov_b32_e32 v6, v2
	v_mov_b32_e32 v7, v2
	v_mov_b32_e32 v8, v2
	v_mov_b32_e32 v9, v2
	v_mov_b32_e32 v10, v2
	v_mov_b32_e32 v11, v2
	v_mov_b32_e32 v12, v2
	v_mov_b32_e32 v13, v2
	v_mov_b32_e32 v18, v2
	v_mov_b32_e32 v19, v2
	v_mov_b32_e32 v20, v2
	v_mov_b32_e32 v21, v2
	v_mov_b32_e32 v26, v2
	v_mov_b32_e32 v27, v2
	v_mov_b32_e32 v28, v2
	v_mov_b32_e32 v29, v2
	v_mov_b32_e32 v34, v2
	v_mov_b32_e32 v35, v2
	v_mov_b32_e32 v36, v2
	v_mov_b32_e32 v37, v2
	v_mov_b32_e32 v42, v2
	v_mov_b32_e32 v43, v2
	v_mov_b32_e32 v44, v2
	v_mov_b32_e32 v45, v2
	v_mov_b32_e32 v50, v2
	v_mov_b32_e32 v51, v2
	v_mov_b32_e32 v52, v2
	v_mov_b32_e32 v53, v2
	v_mov_b32_e32 v58, v2
	v_mov_b32_e32 v59, v2
	v_mov_b32_e32 v60, v2
	v_mov_b32_e32 v61, v2
	v_mov_b32_e32 v70, v2
	v_mov_b32_e32 v71, v2
	v_mov_b32_e32 v72, v2
	v_mov_b32_e32 v73, v2
	v_mov_b32_e32 v78, v2
	v_mov_b32_e32 v79, v2
	v_mov_b32_e32 v80, v2
	v_mov_b32_e32 v81, v2
	v_mov_b32_e32 v86, v2
	v_mov_b32_e32 v87, v2
	v_mov_b32_e32 v88, v2
	v_mov_b32_e32 v89, v2
	v_mov_b32_e32 v94, v2
	v_mov_b32_e32 v95, v2
	v_mov_b32_e32 v96, v2
	v_mov_b32_e32 v97, v2
	v_mov_b32_e32 v102, v2
	v_mov_b32_e32 v103, v2
	v_mov_b32_e32 v104, v2
	v_mov_b32_e32 v105, v2
	v_mov_b32_e32 v110, v2
	v_mov_b32_e32 v111, v2
	v_mov_b32_e32 v112, v2
	v_mov_b32_e32 v113, v2
	v_mov_b32_e32 v122, v2
	v_mov_b32_e32 v123, v2
	v_mov_b32_e32 v124, v2
	v_mov_b32_e32 v125, v2
	v_mov_b32_e32 v126, v2
	v_mov_b32_e32 v127, v2
	v_mov_b32_e32 v128, v2
	v_mov_b32_e32 v129, v2
	v_mov_b32_e32 v66, v2
	v_mov_b32_e32 v67, v2
	v_mov_b32_e32 v68, v2
	v_mov_b32_e32 v69, v2
	v_mov_b32_e32 v74, v2
	v_mov_b32_e32 v75, v2
	v_mov_b32_e32 v76, v2
	v_mov_b32_e32 v77, v2
	v_mov_b32_e32 v82, v2
	v_mov_b32_e32 v83, v2
	v_mov_b32_e32 v84, v2
	v_mov_b32_e32 v85, v2
	v_mov_b32_e32 v90, v2
	v_mov_b32_e32 v91, v2
	v_mov_b32_e32 v92, v2
	v_mov_b32_e32 v93, v2
	v_mov_b32_e32 v98, v2
	v_mov_b32_e32 v99, v2
	v_mov_b32_e32 v100, v2
	v_mov_b32_e32 v101, v2
	v_mov_b32_e32 v106, v2
	v_mov_b32_e32 v107, v2
	v_mov_b32_e32 v108, v2
	v_mov_b32_e32 v109, v2
	v_mov_b32_e32 v114, v2
	v_mov_b32_e32 v115, v2
	v_mov_b32_e32 v116, v2
	v_mov_b32_e32 v117, v2
	v_mov_b32_e32 v118, v2
	v_mov_b32_e32 v119, v2
	v_mov_b32_e32 v120, v2
	v_mov_b32_e32 v121, v2
	v_add_u32_e32 v159, 0x18000, v151
	v_add_u32_e32 v239, 0x1c000, v151
	ds_read_b128 v[160:163], v155
	ds_read_b128 v[164:167], v155 offset:1024
	ds_read_b128 v[168:171], v155 offset:2048
	ds_read_b128 v[172:175], v155 offset:3072
	ds_read_b128 v[176:179], v156
	ds_read_b128 v[180:183], v156 offset:1024
	ds_read_b128 v[184:187], v156 offset:2048
	ds_read_b128 v[188:191], v156 offset:3072
	ds_read_b128 v[192:195], v157
	ds_read_b128 v[196:199], v157 offset:1024
	ds_read_b128 v[200:203], v157 offset:2048
	ds_read_b128 v[204:207], v157 offset:3072
	ds_read_b128 v[208:211], v157 offset:4096
	ds_read_b128 v[212:215], v157 offset:5120
	ds_read_b128 v[216:219], v157 offset:6144
	ds_read_b128 v[220:223], v157 offset:7168
	s_waitcnt lgkmcnt(7)
	v_mfma_f32_16x16x32_bf16 v[118:121], v[160:163], v[192:195], v[118:121]
	v_mfma_f32_16x16x32_bf16 v[114:117], v[168:171], v[192:195], v[114:117]
	v_mfma_f32_16x16x32_bf16 v[126:129], v[176:179], v[192:195], v[126:129]
	v_mfma_f32_16x16x32_bf16 v[122:125], v[184:187], v[192:195], v[122:125]
	s_waitcnt lgkmcnt(5)
	v_mfma_f32_16x16x32_bf16 v[106:109], v[160:163], v[200:203], v[106:109]
	v_mfma_f32_16x16x32_bf16 v[98:101], v[168:171], v[200:203], v[98:101]
	v_mfma_f32_16x16x32_bf16 v[110:113], v[176:179], v[200:203], v[110:113]
	v_mfma_f32_16x16x32_bf16 v[102:105], v[184:187], v[200:203], v[102:105]
	ds_read_b128 v[192:195], v157 offset:16384
	s_waitcnt lgkmcnt(4)
	v_mfma_f32_16x16x32_bf16 v[90:93], v[160:163], v[208:211], v[90:93]
	v_mfma_f32_16x16x32_bf16 v[82:85], v[168:171], v[208:211], v[82:85]
	v_mfma_f32_16x16x32_bf16 v[94:97], v[176:179], v[208:211], v[94:97]
	v_mfma_f32_16x16x32_bf16 v[86:89], v[184:187], v[208:211], v[86:89]
	ds_read_b128 v[200:203], v157 offset:18432
	s_waitcnt lgkmcnt(3)
	v_mfma_f32_16x16x32_bf16 v[74:77], v[160:163], v[216:219], v[74:77]
	v_mfma_f32_16x16x32_bf16 v[66:69], v[168:171], v[216:219], v[66:69]
	v_mfma_f32_16x16x32_bf16 v[78:81], v[176:179], v[216:219], v[78:81]
	v_mfma_f32_16x16x32_bf16 v[70:73], v[184:187], v[216:219], v[70:73]
	ds_read_b128 v[208:211], v157 offset:20480
	s_waitcnt lgkmcnt(9)
	v_mfma_f32_16x16x32_bf16 v[118:121], v[164:167], v[196:199], v[118:121]
	v_mfma_f32_16x16x32_bf16 v[114:117], v[172:175], v[196:199], v[114:117]
	v_mfma_f32_16x16x32_bf16 v[126:129], v[180:183], v[196:199], v[126:129]
	v_mfma_f32_16x16x32_bf16 v[122:125], v[188:191], v[196:199], v[122:125]
	ds_read_b128 v[216:219], v157 offset:22528
	s_waitcnt lgkmcnt(8)
	v_mfma_f32_16x16x32_bf16 v[106:109], v[164:167], v[204:207], v[106:109]
	v_mfma_f32_16x16x32_bf16 v[98:101], v[172:175], v[204:207], v[98:101]
	v_mfma_f32_16x16x32_bf16 v[110:113], v[180:183], v[204:207], v[110:113]
	v_mfma_f32_16x16x32_bf16 v[102:105], v[188:191], v[204:207], v[102:105]
	ds_read_b128 v[196:199], v157 offset:17408
	s_waitcnt lgkmcnt(7)
	v_mfma_f32_16x16x32_bf16 v[90:93], v[164:167], v[212:215], v[90:93]
	v_mfma_f32_16x16x32_bf16 v[82:85], v[172:175], v[212:215], v[82:85]
	v_mfma_f32_16x16x32_bf16 v[94:97], v[180:183], v[212:215], v[94:97]
	v_mfma_f32_16x16x32_bf16 v[86:89], v[188:191], v[212:215], v[86:89]
	ds_read_b128 v[204:207], v157 offset:19456
	s_waitcnt lgkmcnt(6)
	v_mfma_f32_16x16x32_bf16 v[74:77], v[164:167], v[220:223], v[74:77]
	v_mfma_f32_16x16x32_bf16 v[66:69], v[172:175], v[220:223], v[66:69]
	v_mfma_f32_16x16x32_bf16 v[78:81], v[180:183], v[220:223], v[78:81]
	v_mfma_f32_16x16x32_bf16 v[70:73], v[188:191], v[220:223], v[70:73]
	ds_read_b128 v[212:215], v157 offset:21504
.Lswp_loop_p1:
	s_add_u32 s50, s48, 0xfffc0080
	s_addc_u32 s51, s49, -1
	s_cmp_eq_u32 s73, 12
	s_cselect_b32 s53, s27, s51
	s_cselect_b32 s52, s69, s50
	s_cselect_b32 s51, s25, s72
	s_cselect_b32 s50, s70, s71
	s_waitcnt lgkmcnt(6)
	v_mfma_f32_16x16x32_bf16 v[58:61], v[160:163], v[192:195], v[58:61]
	v_mfma_f32_16x16x32_bf16 v[50:53], v[168:171], v[192:195], v[50:53]
	v_mfma_f32_16x16x32_bf16 v[62:65], v[176:179], v[192:195], v[62:65]
	v_mfma_f32_16x16x32_bf16 v[54:57], v[184:187], v[192:195], v[54:57]
	ds_read_b128 v[220:223], v157 offset:23552
	s_waitcnt lgkmcnt(6)
	v_mfma_f32_16x16x32_bf16 v[42:45], v[160:163], v[200:203], v[42:45]
	v_mfma_f32_16x16x32_bf16 v[34:37], v[168:171], v[200:203], v[34:37]
	v_mfma_f32_16x16x32_bf16 v[46:49], v[176:179], v[200:203], v[46:49]
	v_mfma_f32_16x16x32_bf16 v[38:41], v[184:187], v[200:203], v[38:41]
	s_waitcnt lgkmcnt(5)
	v_mfma_f32_16x16x32_bf16 v[26:29], v[160:163], v[208:211], v[26:29]
	v_mfma_f32_16x16x32_bf16 v[18:21], v[168:171], v[208:211], v[18:21]
	v_mfma_f32_16x16x32_bf16 v[30:33], v[176:179], v[208:211], v[30:33]
	v_mfma_f32_16x16x32_bf16 v[22:25], v[184:187], v[208:211], v[22:25]
	s_waitcnt lgkmcnt(4)
	v_mfma_f32_16x16x32_bf16 v[10:13], v[160:163], v[216:219], v[10:13]
	v_mfma_f32_16x16x32_bf16 v[6:9], v[168:171], v[216:219], v[6:9]
	v_mfma_f32_16x16x32_bf16 v[14:17], v[176:179], v[216:219], v[14:17]
	v_mfma_f32_16x16x32_bf16 v[2:5], v[184:187], v[216:219], v[2:5]
	s_waitcnt vmcnt(0) lgkmcnt(0)
	s_barrier
	s_cmp_eq_u64 s[16:17], 0
	s_cbranch_scc1 .Lswp_s0_p1
	s_add_i32 s74, s66, s54
	v_lshl_add_u64 v[148:149], s[50:51], 0, v[134:135]
	s_mov_b32 m0, s74
	s_nop 0
	global_load_lds_dwordx4 v[148:149], off
	s_add_i32 m0, s74, 0x2000
	s_add_u32 s74, s50, 0x40000
	v_lshl_add_u64 v[224:225], s[50:51], 0, v[130:131]
	s_addc_u32 s75, s51, 0
	s_add_i32 s76, s67, s54
	global_load_lds_dwordx4 v[224:225], off
.Lswp_s0_p1:
	s_waitcnt lgkmcnt(3)
	v_mfma_f32_16x16x32_bf16 v[58:61], v[164:167], v[196:199], v[58:61]
	v_mfma_f32_16x16x32_bf16 v[50:53], v[172:175], v[196:199], v[50:53]
	v_mfma_f32_16x16x32_bf16 v[62:65], v[180:183], v[196:199], v[62:65]
	v_mfma_f32_16x16x32_bf16 v[54:57], v[188:191], v[196:199], v[54:57]
	ds_read_b128 v[160:163], v159
	ds_read_b128 v[168:171], v159 offset:2048
	ds_read_b128 v[176:179], v239
	ds_read_b128 v[184:187], v239 offset:2048
	s_cmp_eq_u64 s[16:17], 0
	s_cbranch_scc0 .Lswp_s1_p1
	s_add_i32 s74, s66, s54
	v_lshl_add_u64 v[148:149], s[50:51], 0, v[134:135]
	s_mov_b32 m0, s74
	s_nop 0
	global_load_lds_dwordx4 v[148:149], off
	s_add_i32 m0, s74, 0x2000
	s_add_u32 s74, s50, 0x40000
	v_lshl_add_u64 v[224:225], s[50:51], 0, v[130:131]
	s_addc_u32 s75, s51, 0
	s_add_i32 s76, s67, s54
	global_load_lds_dwordx4 v[224:225], off
.Lswp_s1_p1:
	s_waitcnt lgkmcnt(6)
	v_mfma_f32_16x16x32_bf16 v[42:45], v[164:167], v[204:207], v[42:45]
	v_mfma_f32_16x16x32_bf16 v[34:37], v[172:175], v[204:207], v[34:37]
	v_mfma_f32_16x16x32_bf16 v[46:49], v[180:183], v[204:207], v[46:49]
	v_mfma_f32_16x16x32_bf16 v[38:41], v[188:191], v[204:207], v[38:41]
	ds_read_b128 v[192:195], v157 offset:32768
	s_cmp_eq_u64 s[16:17], 0
	s_cbranch_scc1 .Lswp_s2_p1
	v_lshl_add_u64 v[226:227], s[74:75], 0, v[134:135]
	s_mov_b32 m0, s76
	v_lshl_add_u64 v[228:229], s[52:53], 0, v[132:133]
	global_load_lds_dwordx4 v[226:227], off
	v_lshl_add_u64 v[226:227], s[74:75], 0, v[130:131]
	s_add_i32 m0, s76, 0x2000
	s_nop 0
	global_load_lds_dwordx4 v[226:227], off
.Lswp_s2_p1:
	s_waitcnt lgkmcnt(6)
	v_mfma_f32_16x16x32_bf16 v[26:29], v[164:167], v[212:215], v[26:29]
	v_mfma_f32_16x16x32_bf16 v[18:21], v[172:175], v[212:215], v[18:21]
	v_mfma_f32_16x16x32_bf16 v[30:33], v[180:183], v[212:215], v[30:33]
	v_mfma_f32_16x16x32_bf16 v[22:25], v[188:191], v[212:215], v[22:25]
	ds_read_b128 v[200:203], v157 offset:34816
	s_cmp_eq_u64 s[16:17], 0
	s_cbranch_scc0 .Lswp_s3_p1
	v_lshl_add_u64 v[226:227], s[74:75], 0, v[134:135]
	s_mov_b32 m0, s76
	v_lshl_add_u64 v[228:229], s[52:53], 0, v[132:133]
	global_load_lds_dwordx4 v[226:227], off
	v_lshl_add_u64 v[226:227], s[74:75], 0, v[130:131]
	s_add_i32 m0, s76, 0x2000
	s_nop 0
	global_load_lds_dwordx4 v[226:227], off
.Lswp_s3_p1:
	s_waitcnt lgkmcnt(6)
	v_mfma_f32_16x16x32_bf16 v[10:13], v[164:167], v[220:223], v[10:13]
	v_mfma_f32_16x16x32_bf16 v[6:9], v[172:175], v[220:223], v[6:9]
	v_mfma_f32_16x16x32_bf16 v[14:17], v[180:183], v[220:223], v[14:17]
	v_mfma_f32_16x16x32_bf16 v[2:5], v[188:191], v[220:223], v[2:5]
	ds_read_b128 v[208:211], v157 offset:36864
	s_cmp_eq_u64 s[16:17], 0
	s_cbranch_scc1 .Lswp_s4_p1
	v_lshl_add_u64 v[226:227], s[52:53], 0, v[136:137]
	s_mov_b32 m0, s57
	s_nop 0
	global_load_lds_dwordx4 v[226:227], off
	s_mov_b32 m0, s58
	s_nop 0
	global_load_lds_dwordx4 v[228:229], off
.Lswp_s4_p1:
	s_waitcnt lgkmcnt(2)
	v_mfma_f32_16x16x32_bf16 v[118:121], v[160:163], v[192:195], v[118:121]
	v_mfma_f32_16x16x32_bf16 v[114:117], v[168:171], v[192:195], v[114:117]
	v_mfma_f32_16x16x32_bf16 v[126:129], v[176:179], v[192:195], v[126:129]
	v_mfma_f32_16x16x32_bf16 v[122:125], v[184:187], v[192:195], v[122:125]
	ds_read_b128 v[216:219], v157 offset:38912
	ds_read_b128 v[164:167], v159 offset:1024
	ds_read_b128 v[172:175], v159 offset:3072
	s_cmp_eq_u64 s[16:17], 0
	s_cbranch_scc0 .Lswp_s5_p1
	v_lshl_add_u64 v[226:227], s[52:53], 0, v[136:137]
	s_mov_b32 m0, s57
	s_nop 0
	global_load_lds_dwordx4 v[226:227], off
	s_mov_b32 m0, s58
	s_nop 0
	global_load_lds_dwordx4 v[228:229], off
.Lswp_s5_p1:
	s_waitcnt lgkmcnt(4)
	v_mfma_f32_16x16x32_bf16 v[106:109], v[160:163], v[200:203], v[106:109]
	v_mfma_f32_16x16x32_bf16 v[98:101], v[168:171], v[200:203], v[98:101]
	v_mfma_f32_16x16x32_bf16 v[110:113], v[176:179], v[200:203], v[110:113]
	v_mfma_f32_16x16x32_bf16 v[102:105], v[184:187], v[200:203], v[102:105]
	ds_read_b128 v[196:199], v157 offset:33792
	ds_read_b128 v[180:183], v239 offset:1024
	ds_read_b128 v[188:191], v239 offset:3072
	ds_read_b128 v[192:195], v157 offset:49152
	s_cmp_eq_u64 s[16:17], 0
	s_cbranch_scc1 .Lswp_s6_p1
	s_add_u32 s52, s52, 0x40000
	s_addc_u32 s53, s53, 0
	s_mov_b32 m0, s59
	v_lshl_add_u64 v[230:231], s[52:53], 0, v[136:137]
	global_load_lds_dwordx4 v[230:231], off
	v_lshl_add_u64 v[230:231], s[52:53], 0, v[132:133]
	s_mov_b32 m0, s60
	s_nop 0
	global_load_lds_dwordx4 v[230:231], off
.Lswp_s6_p1:
	s_waitcnt lgkmcnt(7)
	v_mfma_f32_16x16x32_bf16 v[90:93], v[160:163], v[208:211], v[90:93]
	v_mfma_f32_16x16x32_bf16 v[82:85], v[168:171], v[208:211], v[82:85]
	v_mfma_f32_16x16x32_bf16 v[94:97], v[176:179], v[208:211], v[94:97]
	v_mfma_f32_16x16x32_bf16 v[86:89], v[184:187], v[208:211], v[86:89]
	ds_read_b128 v[204:207], v157 offset:35840
	ds_read_b128 v[200:203], v157 offset:51200
	s_cmp_eq_u64 s[16:17], 0
	s_cbranch_scc0 .Lswp_s7_p1
	s_add_u32 s52, s52, 0x40000
	s_addc_u32 s53, s53, 0
	s_mov_b32 m0, s59
	v_lshl_add_u64 v[230:231], s[52:53], 0, v[136:137]
	global_load_lds_dwordx4 v[230:231], off
	v_lshl_add_u64 v[230:231], s[52:53], 0, v[132:133]
	s_mov_b32 m0, s60
	s_nop 0
	global_load_lds_dwordx4 v[230:231], off
.Lswp_s7_p1:
	s_waitcnt lgkmcnt(8)
	v_mfma_f32_16x16x32_bf16 v[74:77], v[160:163], v[216:219], v[74:77]
	v_mfma_f32_16x16x32_bf16 v[66:69], v[168:171], v[216:219], v[66:69]
	v_mfma_f32_16x16x32_bf16 v[78:81], v[176:179], v[216:219], v[78:81]
	v_mfma_f32_16x16x32_bf16 v[70:73], v[184:187], v[216:219], v[70:73]
	ds_read_b128 v[212:215], v157 offset:37888
	ds_read_b128 v[208:211], v157 offset:53248
	s_waitcnt lgkmcnt(5)
	v_mfma_f32_16x16x32_bf16 v[118:121], v[164:167], v[196:199], v[118:121]
	v_mfma_f32_16x16x32_bf16 v[114:117], v[172:175], v[196:199], v[114:117]
	v_mfma_f32_16x16x32_bf16 v[126:129], v[180:183], v[196:199], v[126:129]
	v_mfma_f32_16x16x32_bf16 v[122:125], v[188:191], v[196:199], v[122:125]
	ds_read_b128 v[220:223], v157 offset:39936
	ds_read_b128 v[216:219], v157 offset:55296
	s_waitcnt lgkmcnt(5)
	v_mfma_f32_16x16x32_bf16 v[106:109], v[164:167], v[204:207], v[106:109]
	v_mfma_f32_16x16x32_bf16 v[98:101], v[172:175], v[204:207], v[98:101]
	v_mfma_f32_16x16x32_bf16 v[110:113], v[180:183], v[204:207], v[110:113]
	v_mfma_f32_16x16x32_bf16 v[102:105], v[188:191], v[204:207], v[102:105]
	ds_read_b128 v[196:199], v157 offset:50176
	s_waitcnt lgkmcnt(4)
	v_mfma_f32_16x16x32_bf16 v[90:93], v[164:167], v[212:215], v[90:93]
	v_mfma_f32_16x16x32_bf16 v[82:85], v[172:175], v[212:215], v[82:85]
	v_mfma_f32_16x16x32_bf16 v[94:97], v[180:183], v[212:215], v[94:97]
	v_mfma_f32_16x16x32_bf16 v[86:89], v[188:191], v[212:215], v[86:89]
	ds_read_b128 v[204:207], v157 offset:52224
	s_waitcnt lgkmcnt(3)
	v_mfma_f32_16x16x32_bf16 v[74:77], v[164:167], v[220:223], v[74:77]
	v_mfma_f32_16x16x32_bf16 v[66:69], v[172:175], v[220:223], v[66:69]
	v_mfma_f32_16x16x32_bf16 v[78:81], v[180:183], v[220:223], v[78:81]
	v_mfma_f32_16x16x32_bf16 v[70:73], v[188:191], v[220:223], v[70:73]
	ds_read_b128 v[212:215], v157 offset:54272
	s_cmp_eq_u32 s73, 12
	s_cbranch_scc1 .Lswp_tail_p1
	s_waitcnt lgkmcnt(9)
	v_mfma_f32_16x16x32_bf16 v[58:61], v[160:163], v[192:195], v[58:61]
	v_mfma_f32_16x16x32_bf16 v[50:53], v[168:171], v[192:195], v[50:53]
	v_mfma_f32_16x16x32_bf16 v[62:65], v[176:179], v[192:195], v[62:65]
	v_mfma_f32_16x16x32_bf16 v[54:57], v[184:187], v[192:195], v[54:57]
	ds_read_b128 v[220:223], v157 offset:56320
	s_waitcnt lgkmcnt(8)
	v_mfma_f32_16x16x32_bf16 v[42:45], v[160:163], v[200:203], v[42:45]
	v_mfma_f32_16x16x32_bf16 v[34:37], v[168:171], v[200:203], v[34:37]
	v_mfma_f32_16x16x32_bf16 v[46:49], v[176:179], v[200:203], v[46:49]
	v_mfma_f32_16x16x32_bf16 v[38:41], v[184:187], v[200:203], v[38:41]
	s_waitcnt lgkmcnt(6)
	v_mfma_f32_16x16x32_bf16 v[26:29], v[160:163], v[208:211], v[26:29]
	v_mfma_f32_16x16x32_bf16 v[18:21], v[168:171], v[208:211], v[18:21]
	v_mfma_f32_16x16x32_bf16 v[30:33], v[176:179], v[208:211], v[30:33]
	v_mfma_f32_16x16x32_bf16 v[22:25], v[184:187], v[208:211], v[22:25]
	s_waitcnt lgkmcnt(4)
	v_mfma_f32_16x16x32_bf16 v[10:13], v[160:163], v[216:219], v[10:13]
	v_mfma_f32_16x16x32_bf16 v[6:9], v[168:171], v[216:219], v[6:9]
	v_mfma_f32_16x16x32_bf16 v[14:17], v[176:179], v[216:219], v[14:17]
	v_mfma_f32_16x16x32_bf16 v[2:5], v[184:187], v[216:219], v[2:5]
	s_waitcnt vmcnt(0) lgkmcnt(0)
	s_barrier
	s_add_i32 s74, 0, 0x18000
	s_add_i32 s75, 0, 0x1c000
	s_cmp_eq_u64 s[16:17], 0
	s_cbranch_scc1 .Lswp_s8_p1
	s_add_i32 s52, s74, s54
	v_lshl_add_u64 v[148:149], v[148:149], 0, s[14:15]
	s_mov_b32 m0, s52
	s_nop 0
	global_load_lds_dwordx4 v[148:149], off
	s_add_i32 m0, s52, 0x2000
	s_add_u32 s50, s50, 0x40080
	v_lshl_add_u64 v[148:149], v[224:225], 0, s[14:15]
	s_addc_u32 s51, s51, 0
	s_add_i32 s52, s75, s54
	global_load_lds_dwordx4 v[148:149], off
.Lswp_s8_p1:
	s_waitcnt lgkmcnt(3)
	v_mfma_f32_16x16x32_bf16 v[58:61], v[164:167], v[196:199], v[58:61]
	v_mfma_f32_16x16x32_bf16 v[50:53], v[172:175], v[196:199], v[50:53]
	v_mfma_f32_16x16x32_bf16 v[62:65], v[180:183], v[196:199], v[62:65]
	v_mfma_f32_16x16x32_bf16 v[54:57], v[188:191], v[196:199], v[54:57]
	ds_read_b128 v[160:163], v155
	ds_read_b128 v[168:171], v155 offset:2048
	ds_read_b128 v[176:179], v156
	ds_read_b128 v[184:187], v156 offset:2048
	s_cmp_eq_u64 s[16:17], 0
	s_cbranch_scc0 .Lswp_s9_p1
	s_add_i32 s52, s74, s54
	v_lshl_add_u64 v[148:149], v[148:149], 0, s[14:15]
	s_mov_b32 m0, s52
	s_nop 0
	global_load_lds_dwordx4 v[148:149], off
	s_add_i32 m0, s52, 0x2000
	s_add_u32 s50, s50, 0x40080
	v_lshl_add_u64 v[148:149], v[224:225], 0, s[14:15]
	s_addc_u32 s51, s51, 0
	s_add_i32 s52, s75, s54
	global_load_lds_dwordx4 v[148:149], off
.Lswp_s9_p1:
	s_waitcnt lgkmcnt(6)
	v_mfma_f32_16x16x32_bf16 v[42:45], v[164:167], v[204:207], v[42:45]
	v_mfma_f32_16x16x32_bf16 v[34:37], v[172:175], v[204:207], v[34:37]
	v_mfma_f32_16x16x32_bf16 v[46:49], v[180:183], v[204:207], v[46:49]
	v_mfma_f32_16x16x32_bf16 v[38:41], v[188:191], v[204:207], v[38:41]
	ds_read_b128 v[192:195], v157
	s_cmp_eq_u64 s[16:17], 0
	s_cbranch_scc1 .Lswp_s10_p1
	v_lshl_add_u64 v[148:149], s[50:51], 0, v[134:135]
	s_mov_b32 m0, s52
	s_nop 0
	global_load_lds_dwordx4 v[148:149], off
	v_lshl_add_u64 v[148:149], s[50:51], 0, v[130:131]
	s_add_i32 m0, s52, 0x2000
	s_nop 0
	global_load_lds_dwordx4 v[148:149], off
.Lswp_s10_p1:
	s_waitcnt lgkmcnt(6)
	v_mfma_f32_16x16x32_bf16 v[26:29], v[164:167], v[212:215], v[26:29]
	v_mfma_f32_16x16x32_bf16 v[18:21], v[172:175], v[212:215], v[18:21]
	v_mfma_f32_16x16x32_bf16 v[30:33], v[180:183], v[212:215], v[30:33]
	v_mfma_f32_16x16x32_bf16 v[22:25], v[188:191], v[212:215], v[22:25]
	ds_read_b128 v[200:203], v157 offset:2048
	s_cmp_eq_u64 s[16:17], 0
	s_cbranch_scc0 .Lswp_s11_p1
	v_lshl_add_u64 v[148:149], s[50:51], 0, v[134:135]
	s_mov_b32 m0, s52
	s_nop 0
	global_load_lds_dwordx4 v[148:149], off
	v_lshl_add_u64 v[148:149], s[50:51], 0, v[130:131]
	s_add_i32 m0, s52, 0x2000
	s_nop 0
	global_load_lds_dwordx4 v[148:149], off
.Lswp_s11_p1:
	s_waitcnt lgkmcnt(6)
	v_mfma_f32_16x16x32_bf16 v[10:13], v[164:167], v[220:223], v[10:13]
	v_mfma_f32_16x16x32_bf16 v[6:9], v[172:175], v[220:223], v[6:9]
	v_mfma_f32_16x16x32_bf16 v[14:17], v[180:183], v[220:223], v[14:17]
	v_mfma_f32_16x16x32_bf16 v[2:5], v[188:191], v[220:223], v[2:5]
	ds_read_b128 v[208:211], v157 offset:4096
	s_cmp_eq_u64 s[16:17], 0
	s_cbranch_scc1 .Lswp_s12_p1
	v_lshl_add_u64 v[148:149], v[226:227], 0, s[14:15]
	s_mov_b32 m0, s62
	s_nop 0
	global_load_lds_dwordx4 v[148:149], off
	v_lshl_add_u64 v[148:149], v[228:229], 0, s[14:15]
	s_mov_b32 m0, s63
	s_nop 0
	global_load_lds_dwordx4 v[148:149], off
.Lswp_s12_p1:
	s_waitcnt lgkmcnt(2)
	v_mfma_f32_16x16x32_bf16 v[118:121], v[160:163], v[192:195], v[118:121]
	v_mfma_f32_16x16x32_bf16 v[114:117], v[168:171], v[192:195], v[114:117]
	v_mfma_f32_16x16x32_bf16 v[126:129], v[176:179], v[192:195], v[126:129]
	v_mfma_f32_16x16x32_bf16 v[122:125], v[184:187], v[192:195], v[122:125]
	ds_read_b128 v[216:219], v157 offset:6144
	ds_read_b128 v[164:167], v155 offset:1024
	ds_read_b128 v[172:175], v155 offset:3072
	s_cmp_eq_u64 s[16:17], 0
	s_cbranch_scc0 .Lswp_s13_p1
	v_lshl_add_u64 v[148:149], v[226:227], 0, s[14:15]
	s_mov_b32 m0, s62
	s_nop 0
	global_load_lds_dwordx4 v[148:149], off
	v_lshl_add_u64 v[148:149], v[228:229], 0, s[14:15]
	s_mov_b32 m0, s63
	s_nop 0
	global_load_lds_dwordx4 v[148:149], off
.Lswp_s13_p1:
	s_waitcnt lgkmcnt(4)
	v_mfma_f32_16x16x32_bf16 v[106:109], v[160:163], v[200:203], v[106:109]
	v_mfma_f32_16x16x32_bf16 v[98:101], v[168:171], v[200:203], v[98:101]
	v_mfma_f32_16x16x32_bf16 v[110:113], v[176:179], v[200:203], v[110:113]
	v_mfma_f32_16x16x32_bf16 v[102:105], v[184:187], v[200:203], v[102:105]
	ds_read_b128 v[196:199], v157 offset:1024
	ds_read_b128 v[180:183], v156 offset:1024
	ds_read_b128 v[188:191], v156 offset:3072
	ds_read_b128 v[192:195], v157 offset:16384
	s_cmp_eq_u64 s[16:17], 0
	s_cbranch_scc1 .Lswp_s14_p1
	s_add_i32 s73, s73, 2
	s_add_u32 s48, s48, 0x100
	s_addc_u32 s49, s49, 0
	s_add_u32 s71, s71, 0x100
	s_addc_u32 s72, s72, 0
	v_lshl_add_u64 v[148:149], s[48:49], 0, v[140:141]
	s_add_i32 m0, s57, 0xc000
	s_nop 0
	global_load_lds_dwordx4 v[148:149], off
	v_lshl_add_u64 v[148:149], s[48:49], 0, v[142:143]
	s_add_i32 m0, s57, 0xe000
	s_nop 0
	global_load_lds_dwordx4 v[148:149], off
.Lswp_s14_p1:
	s_waitcnt lgkmcnt(7)
	v_mfma_f32_16x16x32_bf16 v[90:93], v[160:163], v[208:211], v[90:93]
	v_mfma_f32_16x16x32_bf16 v[82:85], v[168:171], v[208:211], v[82:85]
	v_mfma_f32_16x16x32_bf16 v[94:97], v[176:179], v[208:211], v[94:97]
	v_mfma_f32_16x16x32_bf16 v[86:89], v[184:187], v[208:211], v[86:89]
	ds_read_b128 v[204:207], v157 offset:3072
	ds_read_b128 v[200:203], v157 offset:18432
	s_cmp_eq_u64 s[16:17], 0
	s_cbranch_scc0 .Lswp_s15_p1
	s_add_i32 s73, s73, 2
	s_add_u32 s48, s48, 0x100
	s_addc_u32 s49, s49, 0
	s_add_u32 s71, s71, 0x100
	s_addc_u32 s72, s72, 0
	v_lshl_add_u64 v[148:149], s[48:49], 0, v[140:141]
	s_add_i32 m0, s57, 0xc000
	s_nop 0
	global_load_lds_dwordx4 v[148:149], off
	v_lshl_add_u64 v[148:149], s[48:49], 0, v[142:143]
	s_add_i32 m0, s57, 0xe000
	s_nop 0
	global_load_lds_dwordx4 v[148:149], off
.Lswp_s15_p1:
	s_waitcnt lgkmcnt(8)
	v_mfma_f32_16x16x32_bf16 v[74:77], v[160:163], v[216:219], v[74:77]
	v_mfma_f32_16x16x32_bf16 v[66:69], v[168:171], v[216:219], v[66:69]
	v_mfma_f32_16x16x32_bf16 v[78:81], v[176:179], v[216:219], v[78:81]
	v_mfma_f32_16x16x32_bf16 v[70:73], v[184:187], v[216:219], v[70:73]
	ds_read_b128 v[212:215], v157 offset:5120
	ds_read_b128 v[208:211], v157 offset:20480
	s_waitcnt lgkmcnt(5)
	v_mfma_f32_16x16x32_bf16 v[118:121], v[164:167], v[196:199], v[118:121]
	v_mfma_f32_16x16x32_bf16 v[114:117], v[172:175], v[196:199], v[114:117]
	v_mfma_f32_16x16x32_bf16 v[126:129], v[180:183], v[196:199], v[126:129]
	v_mfma_f32_16x16x32_bf16 v[122:125], v[188:191], v[196:199], v[122:125]
	ds_read_b128 v[220:223], v157 offset:7168
	ds_read_b128 v[216:219], v157 offset:22528
	s_waitcnt lgkmcnt(5)
	v_mfma_f32_16x16x32_bf16 v[106:109], v[164:167], v[204:207], v[106:109]
	v_mfma_f32_16x16x32_bf16 v[98:101], v[172:175], v[204:207], v[98:101]
	v_mfma_f32_16x16x32_bf16 v[110:113], v[180:183], v[204:207], v[110:113]
	v_mfma_f32_16x16x32_bf16 v[102:105], v[188:191], v[204:207], v[102:105]
	ds_read_b128 v[196:199], v157 offset:17408
	s_waitcnt lgkmcnt(4)
	v_mfma_f32_16x16x32_bf16 v[90:93], v[164:167], v[212:215], v[90:93]
	v_mfma_f32_16x16x32_bf16 v[82:85], v[172:175], v[212:215], v[82:85]
	v_mfma_f32_16x16x32_bf16 v[94:97], v[180:183], v[212:215], v[94:97]
	v_mfma_f32_16x16x32_bf16 v[86:89], v[188:191], v[212:215], v[86:89]
	ds_read_b128 v[204:207], v157 offset:19456
	s_waitcnt lgkmcnt(3)
	v_mfma_f32_16x16x32_bf16 v[74:77], v[164:167], v[220:223], v[74:77]
	v_mfma_f32_16x16x32_bf16 v[66:69], v[172:175], v[220:223], v[66:69]
	v_mfma_f32_16x16x32_bf16 v[78:81], v[180:183], v[220:223], v[78:81]
	v_mfma_f32_16x16x32_bf16 v[70:73], v[188:191], v[220:223], v[70:73]
	ds_read_b128 v[212:215], v157 offset:21504
	s_branch .Lswp_loop_p1
.Lswp_tail_p1:
	s_waitcnt lgkmcnt(9)
	v_mfma_f32_16x16x32_bf16 v[58:61], v[160:163], v[192:195], v[58:61]
	v_mfma_f32_16x16x32_bf16 v[50:53], v[168:171], v[192:195], v[50:53]
	v_mfma_f32_16x16x32_bf16 v[62:65], v[176:179], v[192:195], v[62:65]
	v_mfma_f32_16x16x32_bf16 v[54:57], v[184:187], v[192:195], v[54:57]
	ds_read_b128 v[220:223], v157 offset:56320
	s_waitcnt lgkmcnt(8)
	v_mfma_f32_16x16x32_bf16 v[42:45], v[160:163], v[200:203], v[42:45]
	v_mfma_f32_16x16x32_bf16 v[34:37], v[168:171], v[200:203], v[34:37]
	v_mfma_f32_16x16x32_bf16 v[46:49], v[176:179], v[200:203], v[46:49]
	v_mfma_f32_16x16x32_bf16 v[38:41], v[184:187], v[200:203], v[38:41]
	s_waitcnt lgkmcnt(6)
	v_mfma_f32_16x16x32_bf16 v[26:29], v[160:163], v[208:211], v[26:29]
	v_mfma_f32_16x16x32_bf16 v[18:21], v[168:171], v[208:211], v[18:21]
	v_mfma_f32_16x16x32_bf16 v[30:33], v[176:179], v[208:211], v[30:33]
	v_mfma_f32_16x16x32_bf16 v[22:25], v[184:187], v[208:211], v[22:25]
	s_waitcnt lgkmcnt(4)
	v_mfma_f32_16x16x32_bf16 v[10:13], v[160:163], v[216:219], v[10:13]
	v_mfma_f32_16x16x32_bf16 v[6:9], v[168:171], v[216:219], v[6:9]
	v_mfma_f32_16x16x32_bf16 v[14:17], v[176:179], v[216:219], v[14:17]
	v_mfma_f32_16x16x32_bf16 v[2:5], v[184:187], v[216:219], v[2:5]
	s_waitcnt vmcnt(0) lgkmcnt(0)
	s_barrier
	s_add_i32 s74, 0, 0x18000
	s_add_i32 s75, 0, 0x1c000
	s_cmp_eq_u64 s[16:17], 0
	s_cbranch_scc1 .Lswp_s16_p1
	s_add_i32 s52, s74, s54
	v_lshl_add_u64 v[148:149], v[148:149], 0, s[14:15]
	s_mov_b32 m0, s52
	s_nop 0
	global_load_lds_dwordx4 v[148:149], off
	s_add_i32 m0, s52, 0x2000
	s_add_u32 s50, s50, 0x40080
	v_lshl_add_u64 v[148:149], v[224:225], 0, s[14:15]
	s_addc_u32 s51, s51, 0
	s_add_i32 s52, s75, s54
	global_load_lds_dwordx4 v[148:149], off
.Lswp_s16_p1:
	s_waitcnt lgkmcnt(3)
	v_mfma_f32_16x16x32_bf16 v[58:61], v[164:167], v[196:199], v[58:61]
	v_mfma_f32_16x16x32_bf16 v[50:53], v[172:175], v[196:199], v[50:53]
	v_mfma_f32_16x16x32_bf16 v[62:65], v[180:183], v[196:199], v[62:65]
	v_mfma_f32_16x16x32_bf16 v[54:57], v[188:191], v[196:199], v[54:57]
	s_cmp_eq_u64 s[16:17], 0
	s_cbranch_scc0 .Lswp_s17_p1
	s_add_i32 s52, s74, s54
	v_lshl_add_u64 v[148:149], v[148:149], 0, s[14:15]
	s_mov_b32 m0, s52
	s_nop 0
	global_load_lds_dwordx4 v[148:149], off
	s_add_i32 m0, s52, 0x2000
	s_add_u32 s50, s50, 0x40080
	v_lshl_add_u64 v[148:149], v[224:225], 0, s[14:15]
	s_addc_u32 s51, s51, 0
	s_add_i32 s52, s75, s54
	global_load_lds_dwordx4 v[148:149], off
.Lswp_s17_p1:
	s_waitcnt lgkmcnt(2)
	v_mfma_f32_16x16x32_bf16 v[42:45], v[164:167], v[204:207], v[42:45]
	v_mfma_f32_16x16x32_bf16 v[34:37], v[172:175], v[204:207], v[34:37]
	v_mfma_f32_16x16x32_bf16 v[46:49], v[180:183], v[204:207], v[46:49]
	v_mfma_f32_16x16x32_bf16 v[38:41], v[188:191], v[204:207], v[38:41]
	s_cmp_eq_u64 s[16:17], 0
	s_cbranch_scc1 .Lswp_s18_p1
	v_lshl_add_u64 v[148:149], s[50:51], 0, v[134:135]
	s_mov_b32 m0, s52
	s_nop 0
	global_load_lds_dwordx4 v[148:149], off
	v_lshl_add_u64 v[148:149], s[50:51], 0, v[130:131]
	s_add_i32 m0, s52, 0x2000
	s_nop 0
	global_load_lds_dwordx4 v[148:149], off
.Lswp_s18_p1:
	s_waitcnt lgkmcnt(1)
	v_mfma_f32_16x16x32_bf16 v[26:29], v[164:167], v[212:215], v[26:29]
	v_mfma_f32_16x16x32_bf16 v[18:21], v[172:175], v[212:215], v[18:21]
	v_mfma_f32_16x16x32_bf16 v[30:33], v[180:183], v[212:215], v[30:33]
	v_mfma_f32_16x16x32_bf16 v[22:25], v[188:191], v[212:215], v[22:25]
	s_cmp_eq_u64 s[16:17], 0
	s_cbranch_scc0 .Lswp_s19_p1
	v_lshl_add_u64 v[148:149], s[50:51], 0, v[134:135]
	s_mov_b32 m0, s52
	s_nop 0
	global_load_lds_dwordx4 v[148:149], off
	v_lshl_add_u64 v[148:149], s[50:51], 0, v[130:131]
	s_add_i32 m0, s52, 0x2000
	s_nop 0
	global_load_lds_dwordx4 v[148:149], off
.Lswp_s19_p1:
	s_waitcnt lgkmcnt(0)
	v_mfma_f32_16x16x32_bf16 v[10:13], v[164:167], v[220:223], v[10:13]
	v_mfma_f32_16x16x32_bf16 v[6:9], v[172:175], v[220:223], v[6:9]
	v_mfma_f32_16x16x32_bf16 v[14:17], v[180:183], v[220:223], v[14:17]
	v_mfma_f32_16x16x32_bf16 v[2:5], v[188:191], v[220:223], v[2:5]
	s_cmp_eq_u64 s[16:17], 0
	s_cbranch_scc1 .Lswp_s20_p1
	v_lshl_add_u64 v[148:149], v[226:227], 0, s[14:15]
	s_mov_b32 m0, s62
	s_nop 0
	global_load_lds_dwordx4 v[148:149], off
	v_lshl_add_u64 v[148:149], v[228:229], 0, s[14:15]
	s_mov_b32 m0, s63
	s_nop 0
	global_load_lds_dwordx4 v[148:149], off
.Lswp_s20_p1:
	s_cmp_eq_u64 s[16:17], 0
	s_cbranch_scc0 .Lswp_s21_p1
	v_lshl_add_u64 v[148:149], v[226:227], 0, s[14:15]
	s_mov_b32 m0, s62
	s_nop 0
	global_load_lds_dwordx4 v[148:149], off
	v_lshl_add_u64 v[148:149], v[228:229], 0, s[14:15]
	s_mov_b32 m0, s63
	s_nop 0
	global_load_lds_dwordx4 v[148:149], off
.Lswp_s21_p1:
	s_cmp_eq_u64 s[16:17], 0
	s_cbranch_scc1 .Lswp_s22_p1
	s_add_u32 s98, s69, 0x40080
	s_addc_u32 s99, s27, 0
	v_lshl_add_u64 v[148:149], s[98:99], 0, v[140:141]
	s_add_i32 m0, s57, 0xc000
	s_nop 0
	global_load_lds_dwordx4 v[148:149], off
	v_lshl_add_u64 v[148:149], s[98:99], 0, v[142:143]
	s_add_i32 m0, s57, 0xe000
	s_nop 0
	global_load_lds_dwordx4 v[148:149], off
.Lswp_s22_p1:
	s_cmp_eq_u64 s[16:17], 0
	s_cbranch_scc0 .Lswp_s23_p1
	s_add_u32 s98, s69, 0x40080
	s_addc_u32 s99, s27, 0
	v_lshl_add_u64 v[148:149], s[98:99], 0, v[140:141]
	s_add_i32 m0, s57, 0xc000
	s_nop 0
	global_load_lds_dwordx4 v[148:149], off
	v_lshl_add_u64 v[148:149], s[98:99], 0, v[142:143]
	s_add_i32 m0, s57, 0xe000
	s_nop 0
	global_load_lds_dwordx4 v[148:149], off
.Lswp_s23_p1:
	s_lshl_b32 s25, s46, 8
	v_add_u32_e32 v148, s25, v150
	v_ashrrev_i32_e32 v149, 31, v148
	v_lshl_add_u64 v[160:161], v[148:149], 2, s[8:9]
	global_load_dword v149, v[160:161], off
	global_load_dword v232, v[160:161], off offset:64
	global_load_dword v233, v[160:161], off offset:128
	global_load_dword v234, v[160:161], off offset:192
	global_load_dword v235, v[160:161], off offset:512
	global_load_dword v236, v[160:161], off offset:576
	global_load_dword v237, v[160:161], off offset:640
	global_load_dword v238, v[160:161], off offset:704
	s_and_b64 vcc, exec, s[16:17]
	s_cbranch_vccz .LBB0_155
.LBB0_155:
	v_pk_mul_f32 v[128:129], v[120:121], v[128:129]
	v_pk_mul_f32 v[126:127], v[118:119], v[126:127]
	v_pk_mul_f32 v[124:125], v[116:117], v[124:125]
	v_pk_mul_f32 v[160:161], v[114:115], v[122:123]
	v_add_u32_e32 v162, s25, v152
	s_lshl_b32 s46, s47, 7
	v_mov_b64_e32 v[122:123], s[12:13]
	s_ashr_i32 s47, s46, 31
	v_mad_i64_i32 v[164:165], s[48:49], v148, s68, v[122:123]
	s_lshl_b64 s[46:47], s[46:47], 1
	v_lshl_add_u64 v[164:165], v[164:165], 0, s[46:47]
	v_lshl_add_u64 v[164:165], v[164:165], 0, v[138:139]
	v_pk_mul_f32 v[112:113], v[108:109], v[112:113]
	v_pk_mul_f32 v[110:111], v[106:107], v[110:111]
	v_pk_mul_f32 v[104:105], v[100:101], v[104:105]
	v_pk_mul_f32 v[102:103], v[98:99], v[102:103]
	v_pk_mul_f32 v[96:97], v[92:93], v[96:97]
	v_pk_mul_f32 v[94:95], v[90:91], v[94:95]
	v_pk_mul_f32 v[88:89], v[84:85], v[88:89]
	v_pk_mul_f32 v[86:87], v[82:83], v[86:87]
	v_pk_mul_f32 v[80:81], v[76:77], v[80:81]
	v_pk_mul_f32 v[78:79], v[74:75], v[78:79]
	v_pk_mul_f32 v[72:73], v[68:69], v[72:73]
	v_pk_mul_f32 v[70:71], v[66:67], v[70:71]
	v_pk_mul_f32 v[64:65], v[60:61], v[64:65]
	v_pk_mul_f32 v[62:63], v[58:59], v[62:63]
	v_pk_mul_f32 v[56:57], v[52:53], v[56:57]
	v_pk_mul_f32 v[54:55], v[50:51], v[54:55]
	v_pk_mul_f32 v[48:49], v[44:45], v[48:49]
	v_pk_mul_f32 v[46:47], v[42:43], v[46:47]
	v_pk_mul_f32 v[40:41], v[36:37], v[40:41]
	v_pk_mul_f32 v[38:39], v[34:35], v[38:39]
	v_pk_mul_f32 v[32:33], v[28:29], v[32:33]
	v_pk_mul_f32 v[30:31], v[26:27], v[30:31]
	v_pk_mul_f32 v[24:25], v[20:21], v[24:25]
	v_pk_mul_f32 v[22:23], v[18:19], v[22:23]
	v_pk_mul_f32 v[16:17], v[12:13], v[16:17]
	v_pk_mul_f32 v[14:15], v[10:11], v[14:15]
	v_pk_mul_f32 v[4:5], v[8:9], v[4:5]
	v_pk_mul_f32 v[2:3], v[6:7], v[2:3]
	s_andn2_b64 vcc, exec, s[4:5]
	s_waitcnt vmcnt(0)
	v_fmamk_f32 v149, v149, 0x3a800000, v158
	v_rsq_f32_e32 v149, v149
	s_nop 0
	v_mul_f32_e32 v168, 0xbfb8aa3b, v149
	v_pk_mul_f32 v[120:121], v[120:121], v[168:169] op_sel_hi:[1,0]
	v_pk_mul_f32 v[118:119], v[118:119], v[168:169] op_sel_hi:[1,0]
	v_pk_mul_f32 v[116:117], v[116:117], v[168:169] op_sel_hi:[1,0]
	v_pk_mul_f32 v[114:115], v[114:115], v[168:169] op_sel_hi:[1,0]
	v_exp_f32_e32 v118, v118
	v_exp_f32_e32 v119, v119
	v_exp_f32_e32 v120, v120
	v_exp_f32_e32 v121, v121
	v_exp_f32_e32 v114, v114
	v_exp_f32_e32 v115, v115
	v_exp_f32_e32 v116, v116
	v_exp_f32_e32 v117, v117
	v_mul_f32_e32 v170, v149, v149
	v_add_f32_e32 v118, 1.0, v118
	v_add_f32_e32 v119, 1.0, v119
	v_add_f32_e32 v120, 1.0, v120
	v_add_f32_e32 v121, 1.0, v121
	v_add_f32_e32 v149, 1.0, v114
	v_add_f32_e32 v159, 1.0, v115
	v_add_f32_e32 v163, 1.0, v116
	v_add_f32_e32 v168, 1.0, v117
	v_rcp_f32_e32 v114, v118
	v_rcp_f32_e32 v115, v119
	v_rcp_f32_e32 v116, v120
	v_rcp_f32_e32 v117, v121
	v_rcp_f32_e32 v118, v149
	v_rcp_f32_e32 v119, v159
	v_rcp_f32_e32 v120, v163
	v_rcp_f32_e32 v121, v168
	v_pk_mul_f32 v[114:115], v[170:171], v[114:115] op_sel_hi:[0,1]
	v_pk_mul_f32 v[116:117], v[170:171], v[116:117] op_sel_hi:[0,1]
	v_pk_mul_f32 v[118:119], v[170:171], v[118:119] op_sel_hi:[0,1]
	v_pk_mul_f32 v[120:121], v[170:171], v[120:121] op_sel_hi:[0,1]
	v_pk_mul_f32 v[116:117], v[128:129], v[116:117]
	v_pk_mul_f32 v[114:115], v[126:127], v[114:115]
	v_pk_mul_f32 v[120:121], v[124:125], v[120:121]
	v_pk_mul_f32 v[118:119], v[160:161], v[118:119]
	v_cvt_pk_bf16_f32 v114, v114, v115
	v_cvt_pk_bf16_f32 v115, v116, v117
	v_cvt_pk_bf16_f32 v116, v118, v119
	v_cvt_pk_bf16_f32 v117, v120, v121
	global_store_dwordx4 v[164:165], v[114:117], off
	v_fmamk_f32 v118, v232, 0x3a800000, v158
	v_rsq_f32_e32 v121, v118
	v_add_u32_e32 v114, s25, v153
	v_mul_f32_e32 v120, 0xbfb8aa3b, v121
	v_pk_mul_f32 v[108:109], v[108:109], v[120:121] op_sel_hi:[1,0]
	v_pk_mul_f32 v[106:107], v[106:107], v[120:121] op_sel_hi:[1,0]
	v_pk_mul_f32 v[100:101], v[100:101], v[120:121] op_sel_hi:[1,0]
	v_pk_mul_f32 v[98:99], v[98:99], v[120:121] op_sel_hi:[1,0]
	v_exp_f32_e32 v106, v106
	v_exp_f32_e32 v107, v107
	v_exp_f32_e32 v108, v108
	v_exp_f32_e32 v109, v109
	v_exp_f32_e32 v98, v98
	v_exp_f32_e32 v99, v99
	v_exp_f32_e32 v100, v100
	v_exp_f32_e32 v101, v101
	v_mul_f32_e32 v124, v121, v121
	v_add_f32_e32 v106, 1.0, v106
	v_add_f32_e32 v107, 1.0, v107
	v_add_f32_e32 v108, 1.0, v108
	v_add_f32_e32 v109, 1.0, v109
	v_add_f32_e32 v115, 1.0, v98
	v_add_f32_e32 v120, 1.0, v99
	v_add_f32_e32 v121, 1.0, v100
	v_add_f32_e32 v125, 1.0, v101
	v_rcp_f32_e32 v98, v106
	v_rcp_f32_e32 v99, v107
	v_rcp_f32_e32 v100, v108
	v_rcp_f32_e32 v101, v109
	v_rcp_f32_e32 v106, v115
	v_rcp_f32_e32 v107, v120
	v_rcp_f32_e32 v108, v121
	v_rcp_f32_e32 v109, v125
	v_mad_i64_i32 v[116:117], s[48:49], v162, s68, v[122:123]
	v_pk_mul_f32 v[98:99], v[124:125], v[98:99] op_sel_hi:[0,1]
	v_pk_mul_f32 v[100:101], v[124:125], v[100:101] op_sel_hi:[0,1]
	v_pk_mul_f32 v[106:107], v[124:125], v[106:107] op_sel_hi:[0,1]
	v_pk_mul_f32 v[108:109], v[124:125], v[108:109] op_sel_hi:[0,1]
	v_lshl_add_u64 v[116:117], v[116:117], 0, s[46:47]
	v_pk_mul_f32 v[100:101], v[112:113], v[100:101]
	v_pk_mul_f32 v[98:99], v[110:111], v[98:99]
	v_pk_mul_f32 v[104:105], v[104:105], v[108:109]
	v_pk_mul_f32 v[102:103], v[102:103], v[106:107]
	v_lshl_add_u64 v[116:117], v[116:117], 0, v[138:139]
	v_cvt_pk_bf16_f32 v98, v98, v99
	v_cvt_pk_bf16_f32 v99, v100, v101
	v_cvt_pk_bf16_f32 v100, v102, v103
	v_cvt_pk_bf16_f32 v101, v104, v105
	global_store_dwordx4 v[116:117], v[98:101], off
	v_fmamk_f32 v102, v233, 0x3a800000, v158
	v_rsq_f32_e32 v105, v102
	v_add_u32_e32 v98, s25, v154
	v_mul_f32_e32 v104, 0xbfb8aa3b, v105
	v_pk_mul_f32 v[92:93], v[92:93], v[104:105] op_sel_hi:[1,0]
	v_pk_mul_f32 v[90:91], v[90:91], v[104:105] op_sel_hi:[1,0]
	v_pk_mul_f32 v[84:85], v[84:85], v[104:105] op_sel_hi:[1,0]
	v_pk_mul_f32 v[82:83], v[82:83], v[104:105] op_sel_hi:[1,0]
	v_exp_f32_e32 v90, v90
	v_exp_f32_e32 v91, v91
	v_exp_f32_e32 v92, v92
	v_exp_f32_e32 v93, v93
	v_exp_f32_e32 v82, v82
	v_exp_f32_e32 v83, v83
	v_exp_f32_e32 v84, v84
	v_exp_f32_e32 v85, v85
	v_mul_f32_e32 v106, v105, v105
	v_add_f32_e32 v90, 1.0, v90
	v_add_f32_e32 v91, 1.0, v91
	v_add_f32_e32 v92, 1.0, v92
	v_add_f32_e32 v93, 1.0, v93
	v_add_f32_e32 v99, 1.0, v82
	v_add_f32_e32 v104, 1.0, v83
	v_add_f32_e32 v105, 1.0, v84
	v_add_f32_e32 v107, 1.0, v85
	v_rcp_f32_e32 v82, v90
	v_rcp_f32_e32 v83, v91
	v_rcp_f32_e32 v84, v92
	v_rcp_f32_e32 v85, v93
	v_rcp_f32_e32 v90, v99
	v_rcp_f32_e32 v91, v104
	v_rcp_f32_e32 v92, v105
	v_rcp_f32_e32 v93, v107
	v_mad_i64_i32 v[100:101], s[48:49], v114, s68, v[122:123]
	v_pk_mul_f32 v[82:83], v[106:107], v[82:83] op_sel_hi:[0,1]
	v_pk_mul_f32 v[84:85], v[106:107], v[84:85] op_sel_hi:[0,1]
	v_pk_mul_f32 v[90:91], v[106:107], v[90:91] op_sel_hi:[0,1]
	v_pk_mul_f32 v[92:93], v[106:107], v[92:93] op_sel_hi:[0,1]
	v_lshl_add_u64 v[100:101], v[100:101], 0, s[46:47]
	v_pk_mul_f32 v[84:85], v[96:97], v[84:85]
	v_pk_mul_f32 v[82:83], v[94:95], v[82:83]
	v_pk_mul_f32 v[88:89], v[88:89], v[92:93]
	v_pk_mul_f32 v[86:87], v[86:87], v[90:91]
	v_lshl_add_u64 v[100:101], v[100:101], 0, v[138:139]
	v_cvt_pk_bf16_f32 v82, v82, v83
	v_cvt_pk_bf16_f32 v83, v84, v85
	v_cvt_pk_bf16_f32 v84, v86, v87
	v_cvt_pk_bf16_f32 v85, v88, v89
	global_store_dwordx4 v[100:101], v[82:85], off
	s_nop 0
	s_nop 0
	v_add_u32_e32 v84, 0x80, v148
	v_mad_i64_i32 v[82:83], s[48:49], v98, s68, v[122:123]
	v_lshl_add_u64 v[82:83], v[82:83], 0, s[46:47]
	v_lshl_add_u64 v[82:83], v[82:83], 0, v[138:139]
	v_fmamk_f32 v85, v234, 0x3a800000, v158
	v_rsq_f32_e32 v89, v85
	s_nop 0
	v_mul_f32_e32 v88, 0xbfb8aa3b, v89
	v_pk_mul_f32 v[76:77], v[76:77], v[88:89] op_sel_hi:[1,0]
	v_pk_mul_f32 v[74:75], v[74:75], v[88:89] op_sel_hi:[1,0]
	v_pk_mul_f32 v[68:69], v[68:69], v[88:89] op_sel_hi:[1,0]
	v_pk_mul_f32 v[66:67], v[66:67], v[88:89] op_sel_hi:[1,0]
	v_exp_f32_e32 v74, v74
	v_exp_f32_e32 v75, v75
	v_exp_f32_e32 v76, v76
	v_exp_f32_e32 v77, v77
	v_exp_f32_e32 v66, v66
	v_exp_f32_e32 v67, v67
	v_exp_f32_e32 v68, v68
	v_exp_f32_e32 v69, v69
	v_mul_f32_e32 v90, v89, v89
	v_add_f32_e32 v74, 1.0, v74
	v_add_f32_e32 v75, 1.0, v75
	v_add_f32_e32 v76, 1.0, v76
	v_add_f32_e32 v77, 1.0, v77
	v_add_f32_e32 v85, 1.0, v66
	v_add_f32_e32 v88, 1.0, v67
	v_add_f32_e32 v89, 1.0, v68
	v_add_f32_e32 v91, 1.0, v69
	v_rcp_f32_e32 v66, v74
	v_rcp_f32_e32 v67, v75
	v_rcp_f32_e32 v68, v76
	v_rcp_f32_e32 v69, v77
	v_rcp_f32_e32 v74, v85
	v_rcp_f32_e32 v75, v88
	v_rcp_f32_e32 v76, v89
	v_rcp_f32_e32 v77, v91
	v_pk_mul_f32 v[66:67], v[90:91], v[66:67] op_sel_hi:[0,1]
	v_pk_mul_f32 v[68:69], v[90:91], v[68:69] op_sel_hi:[0,1]
	v_pk_mul_f32 v[74:75], v[90:91], v[74:75] op_sel_hi:[0,1]
	v_pk_mul_f32 v[76:77], v[90:91], v[76:77] op_sel_hi:[0,1]
	v_pk_mul_f32 v[68:69], v[80:81], v[68:69]
	v_pk_mul_f32 v[66:67], v[78:79], v[66:67]
	v_pk_mul_f32 v[72:73], v[72:73], v[76:77]
	v_pk_mul_f32 v[70:71], v[70:71], v[74:75]
	v_cvt_pk_bf16_f32 v66, v66, v67
	v_cvt_pk_bf16_f32 v67, v68, v69
	v_cvt_pk_bf16_f32 v68, v70, v71
	v_cvt_pk_bf16_f32 v69, v72, v73
	global_store_dwordx4 v[82:83], v[66:69], off
	v_fmamk_f32 v70, v235, 0x3a800000, v158
	v_rsq_f32_e32 v73, v70
	v_add_u32_e32 v66, 0x90, v148
	v_mul_f32_e32 v72, 0xbfb8aa3b, v73
	v_pk_mul_f32 v[60:61], v[60:61], v[72:73] op_sel_hi:[1,0]
	v_pk_mul_f32 v[58:59], v[58:59], v[72:73] op_sel_hi:[1,0]
	v_pk_mul_f32 v[52:53], v[52:53], v[72:73] op_sel_hi:[1,0]
	v_pk_mul_f32 v[50:51], v[50:51], v[72:73] op_sel_hi:[1,0]
	v_exp_f32_e32 v58, v58
	v_exp_f32_e32 v59, v59
	v_exp_f32_e32 v60, v60
	v_exp_f32_e32 v61, v61
	v_exp_f32_e32 v50, v50
	v_exp_f32_e32 v51, v51
	v_exp_f32_e32 v52, v52
	v_exp_f32_e32 v53, v53
	v_mul_f32_e32 v74, v73, v73
	v_add_f32_e32 v58, 1.0, v58
	v_add_f32_e32 v59, 1.0, v59
	v_add_f32_e32 v60, 1.0, v60
	v_add_f32_e32 v61, 1.0, v61
	v_add_f32_e32 v67, 1.0, v50
	v_add_f32_e32 v72, 1.0, v51
	v_add_f32_e32 v73, 1.0, v52
	v_add_f32_e32 v75, 1.0, v53
	v_rcp_f32_e32 v50, v58
	v_rcp_f32_e32 v51, v59
	v_rcp_f32_e32 v52, v60
	v_rcp_f32_e32 v53, v61
	v_rcp_f32_e32 v58, v67
	v_rcp_f32_e32 v59, v72
	v_rcp_f32_e32 v60, v73
	v_rcp_f32_e32 v61, v75
	v_mad_i64_i32 v[68:69], s[48:49], v84, s68, v[122:123]
	v_pk_mul_f32 v[50:51], v[74:75], v[50:51] op_sel_hi:[0,1]
	v_pk_mul_f32 v[52:53], v[74:75], v[52:53] op_sel_hi:[0,1]
	v_pk_mul_f32 v[58:59], v[74:75], v[58:59] op_sel_hi:[0,1]
	v_pk_mul_f32 v[60:61], v[74:75], v[60:61] op_sel_hi:[0,1]
	v_lshl_add_u64 v[68:69], v[68:69], 0, s[46:47]
	v_pk_mul_f32 v[52:53], v[64:65], v[52:53]
	v_pk_mul_f32 v[50:51], v[62:63], v[50:51]
	v_pk_mul_f32 v[56:57], v[56:57], v[60:61]
	v_pk_mul_f32 v[54:55], v[54:55], v[58:59]
	v_lshl_add_u64 v[68:69], v[68:69], 0, v[138:139]
	v_cvt_pk_bf16_f32 v50, v50, v51
	v_cvt_pk_bf16_f32 v51, v52, v53
	v_cvt_pk_bf16_f32 v52, v54, v55
	v_cvt_pk_bf16_f32 v53, v56, v57
	global_store_dwordx4 v[68:69], v[50:53], off
	v_fmamk_f32 v54, v236, 0x3a800000, v158
	v_rsq_f32_e32 v57, v54
	v_add_u32_e32 v50, 0xa0, v148
	v_mul_f32_e32 v56, 0xbfb8aa3b, v57
	v_pk_mul_f32 v[44:45], v[44:45], v[56:57] op_sel_hi:[1,0]
	v_pk_mul_f32 v[42:43], v[42:43], v[56:57] op_sel_hi:[1,0]
	v_pk_mul_f32 v[36:37], v[36:37], v[56:57] op_sel_hi:[1,0]
	v_pk_mul_f32 v[34:35], v[34:35], v[56:57] op_sel_hi:[1,0]
	v_exp_f32_e32 v42, v42
	v_exp_f32_e32 v43, v43
	v_exp_f32_e32 v44, v44
	v_exp_f32_e32 v45, v45
	v_exp_f32_e32 v34, v34
	v_exp_f32_e32 v35, v35
	v_exp_f32_e32 v36, v36
	v_exp_f32_e32 v37, v37
	v_mul_f32_e32 v58, v57, v57
	v_add_f32_e32 v42, 1.0, v42
	v_add_f32_e32 v43, 1.0, v43
	v_add_f32_e32 v44, 1.0, v44
	v_add_f32_e32 v45, 1.0, v45
	v_add_f32_e32 v51, 1.0, v34
	v_add_f32_e32 v56, 1.0, v35
	v_add_f32_e32 v57, 1.0, v36
	v_add_f32_e32 v59, 1.0, v37
	v_rcp_f32_e32 v34, v42
	v_rcp_f32_e32 v35, v43
	v_rcp_f32_e32 v36, v44
	v_rcp_f32_e32 v37, v45
	v_rcp_f32_e32 v42, v51
	v_rcp_f32_e32 v43, v56
	v_rcp_f32_e32 v44, v57
	v_rcp_f32_e32 v45, v59
	v_mad_i64_i32 v[52:53], s[48:49], v66, s68, v[122:123]
	v_pk_mul_f32 v[34:35], v[58:59], v[34:35] op_sel_hi:[0,1]
	v_pk_mul_f32 v[36:37], v[58:59], v[36:37] op_sel_hi:[0,1]
	v_pk_mul_f32 v[42:43], v[58:59], v[42:43] op_sel_hi:[0,1]
	v_pk_mul_f32 v[44:45], v[58:59], v[44:45] op_sel_hi:[0,1]
	v_lshl_add_u64 v[52:53], v[52:53], 0, s[46:47]
	v_pk_mul_f32 v[36:37], v[48:49], v[36:37]
	v_pk_mul_f32 v[34:35], v[46:47], v[34:35]
	v_pk_mul_f32 v[40:41], v[40:41], v[44:45]
	v_pk_mul_f32 v[38:39], v[38:39], v[42:43]
	v_lshl_add_u64 v[52:53], v[52:53], 0, v[138:139]
	v_cvt_pk_bf16_f32 v34, v34, v35
	v_cvt_pk_bf16_f32 v35, v36, v37
	v_cvt_pk_bf16_f32 v36, v38, v39
	v_cvt_pk_bf16_f32 v37, v40, v41
	global_store_dwordx4 v[52:53], v[34:37], off
	v_fmamk_f32 v38, v237, 0x3a800000, v158
	v_rsq_f32_e32 v41, v38
	v_add_u32_e32 v34, 0xb0, v148
	v_mul_f32_e32 v40, 0xbfb8aa3b, v41
	v_pk_mul_f32 v[28:29], v[28:29], v[40:41] op_sel_hi:[1,0]
	v_pk_mul_f32 v[26:27], v[26:27], v[40:41] op_sel_hi:[1,0]
	v_pk_mul_f32 v[20:21], v[20:21], v[40:41] op_sel_hi:[1,0]
	v_pk_mul_f32 v[18:19], v[18:19], v[40:41] op_sel_hi:[1,0]
	v_exp_f32_e32 v26, v26
	v_exp_f32_e32 v27, v27
	v_exp_f32_e32 v28, v28
	v_exp_f32_e32 v29, v29
	v_exp_f32_e32 v18, v18
	v_exp_f32_e32 v19, v19
	v_exp_f32_e32 v20, v20
	v_exp_f32_e32 v21, v21
	v_mul_f32_e32 v42, v41, v41
	v_add_f32_e32 v26, 1.0, v26
	v_add_f32_e32 v27, 1.0, v27
	v_add_f32_e32 v28, 1.0, v28
	v_add_f32_e32 v29, 1.0, v29
	v_add_f32_e32 v35, 1.0, v18
	v_add_f32_e32 v40, 1.0, v19
	v_add_f32_e32 v41, 1.0, v20
	v_add_f32_e32 v43, 1.0, v21
	v_rcp_f32_e32 v18, v26
	v_rcp_f32_e32 v19, v27
	v_rcp_f32_e32 v20, v28
	v_rcp_f32_e32 v21, v29
	v_rcp_f32_e32 v26, v35
	v_rcp_f32_e32 v27, v40
	v_rcp_f32_e32 v28, v41
	v_rcp_f32_e32 v29, v43
	v_mad_i64_i32 v[36:37], s[48:49], v50, s68, v[122:123]
	v_pk_mul_f32 v[18:19], v[42:43], v[18:19] op_sel_hi:[0,1]
	v_pk_mul_f32 v[20:21], v[42:43], v[20:21] op_sel_hi:[0,1]
	v_pk_mul_f32 v[26:27], v[42:43], v[26:27] op_sel_hi:[0,1]
	v_pk_mul_f32 v[28:29], v[42:43], v[28:29] op_sel_hi:[0,1]
	v_lshl_add_u64 v[36:37], v[36:37], 0, s[46:47]
	v_pk_mul_f32 v[20:21], v[32:33], v[20:21]
	v_pk_mul_f32 v[18:19], v[30:31], v[18:19]
	v_pk_mul_f32 v[24:25], v[24:25], v[28:29]
	v_pk_mul_f32 v[22:23], v[22:23], v[26:27]
	v_lshl_add_u64 v[36:37], v[36:37], 0, v[138:139]
	v_cvt_pk_bf16_f32 v18, v18, v19
	v_cvt_pk_bf16_f32 v19, v20, v21
	v_cvt_pk_bf16_f32 v20, v22, v23
	v_cvt_pk_bf16_f32 v21, v24, v25
	global_store_dwordx4 v[36:37], v[18:21], off
	s_nop 0
	s_nop 0
	v_fmamk_f32 v18, v238, 0x3a800000, v158
	v_rsq_f32_e32 v21, v18
	v_mad_i64_i32 v[18:19], s[4:5], v34, s68, v[122:123]
	v_lshl_add_u64 v[18:19], v[18:19], 0, s[46:47]
	v_mul_f32_e32 v20, 0xbfb8aa3b, v21
	v_pk_mul_f32 v[12:13], v[12:13], v[20:21] op_sel_hi:[1,0]
	v_pk_mul_f32 v[10:11], v[10:11], v[20:21] op_sel_hi:[1,0]
	v_pk_mul_f32 v[8:9], v[8:9], v[20:21] op_sel_hi:[1,0]
	v_pk_mul_f32 v[6:7], v[6:7], v[20:21] op_sel_hi:[1,0]
	v_exp_f32_e32 v10, v10
	v_exp_f32_e32 v11, v11
	v_exp_f32_e32 v12, v12
	v_exp_f32_e32 v13, v13
	v_exp_f32_e32 v6, v6
	v_exp_f32_e32 v7, v7
	v_exp_f32_e32 v8, v8
	v_exp_f32_e32 v9, v9
	v_mul_f32_e32 v22, v21, v21
	v_add_f32_e32 v10, 1.0, v10
	v_add_f32_e32 v11, 1.0, v11
	v_add_f32_e32 v12, 1.0, v12
	v_add_f32_e32 v13, 1.0, v13
	v_add_f32_e32 v20, 1.0, v6
	v_add_f32_e32 v21, 1.0, v7
	v_add_f32_e32 v23, 1.0, v8
	v_add_f32_e32 v24, 1.0, v9
	v_rcp_f32_e32 v6, v10
	v_rcp_f32_e32 v7, v11
	v_rcp_f32_e32 v8, v12
	v_rcp_f32_e32 v9, v13
	v_rcp_f32_e32 v10, v20
	v_rcp_f32_e32 v11, v21
	v_rcp_f32_e32 v12, v23
	v_rcp_f32_e32 v13, v24
	v_pk_mul_f32 v[6:7], v[22:23], v[6:7] op_sel_hi:[0,1]
	v_pk_mul_f32 v[8:9], v[22:23], v[8:9] op_sel_hi:[0,1]
	v_pk_mul_f32 v[10:11], v[22:23], v[10:11] op_sel_hi:[0,1]
	v_pk_mul_f32 v[12:13], v[22:23], v[12:13] op_sel_hi:[0,1]
	v_pk_mul_f32 v[8:9], v[16:17], v[8:9]
	v_pk_mul_f32 v[6:7], v[14:15], v[6:7]
	v_pk_mul_f32 v[12:13], v[4:5], v[12:13]
	v_pk_mul_f32 v[4:5], v[2:3], v[10:11]
	v_lshl_add_u64 v[18:19], v[18:19], 0, v[138:139]
	v_cvt_pk_bf16_f32 v2, v6, v7
	v_cvt_pk_bf16_f32 v3, v8, v9
	v_cvt_pk_bf16_f32 v4, v4, v5
	v_cvt_pk_bf16_f32 v5, v12, v13
	s_mov_b64 s[4:5], -1
	global_store_dwordx4 v[18:19], v[2:5], off
	s_cbranch_vccnz .LBB0_148
	s_andn2_b64 vcc, exec, s[10:11]
	s_cbranch_vccnz .LBB0_147
	s_branch .LBB0_147

.LBB0_834:
	s_waitcnt lgkmcnt(0)
	s_add_u32 s10, s10, 0x40000
	s_addc_u32 s11, s11, 0
	s_add_u32 s12, s4, 0xa400000
	s_addc_u32 s13, s5, 0
	s_lshl_b32 s4, s14, 5
	s_mov_b64 s[14:15], 0x80
	s_and_b32 s26, s4, 0x60
	s_add_i32 m0, s57, 0x18000
	v_lshl_add_u64 v[8:9], v[8:9], 0, s[14:15]
	s_lshl_b32 s25, s24, 13
	s_lshl_b32 s27, s26, 7
	s_waitcnt vmcnt(2)
	global_load_lds_dwordx4 v[8:9], off
	v_lshl_add_u64 v[6:7], v[6:7], 0, s[14:15]
	s_add_i32 m0, s57, 0x1a000
	s_add_i32 s62, s57, 0x8000
	s_add_i32 s63, s57, 0xa000
	global_load_lds_dwordx4 v[6:7], off
	v_lshl_add_u64 v[2:3], v[2:3], 0, s[14:15]
	s_mov_b32 m0, s62
	s_add_u32 s4, s50, 0x40080
	global_load_lds_dwordx4 v[2:3], off
	v_lshl_add_u64 v[2:3], v[4:5], 0, s[14:15]
	s_mov_b32 m0, s63
	s_addc_u32 s5, s51, 0
	global_load_lds_dwordx4 v[2:3], off
	s_add_i32 m0, s57, 0x1c000
	v_lshl_add_u64 v[2:3], s[4:5], 0, v[134:135]
	global_load_lds_dwordx4 v[2:3], off
	v_lshl_add_u64 v[2:3], s[4:5], 0, v[130:131]
	s_add_i32 m0, s57, 0x1e000
	s_cmpk_lt_u32 s17, 0x100
	global_load_lds_dwordx4 v[2:3], off
	v_lshrrev_b32_e32 v3, 1, v10
	v_and_b32_e32 v3, 24, v3
	v_and_b32_e32 v2, 15, v10
	v_lshlrev_b32_e32 v4, 1, v3
	v_lshl_or_b32 v150, s24, 6, v2
	v_lshl_or_b32 v2, v2, 6, v4
	v_lshlrev_b32_e32 v4, 2, v10
	v_and_b32_e32 v4, 32, v4
	v_bitop3_b32 v5, v2, s25, v4 bitop3:0xde
	v_bitop3_b32 v151, v2, s27, v4 bitop3:0xde
	v_or_b32_e32 v2, s26, v3
	v_lshlrev_b32_e32 v3, 14, v15
	v_and_b32_e32 v3, 0xffff8000, v3
	v_lshl_add_u32 v3, v14, 11, v3
	v_and_b32_e32 v4, 1, v15
	v_lshl_or_b32 v3, v4, 6, v3
	v_lshl_add_u32 v140, v16, 1, v3
	v_lshlrev_b32_e32 v3, 14, v11
	v_and_b32_e32 v3, 0xffff8000, v3
	s_waitcnt vmcnt(6)
	v_lshl_add_u32 v3, v12, 11, v3
	v_and_b32_e32 v4, 1, v11
	s_sext_i32_i16 s47, s16
	s_cselect_b64 s[16:17], -1, 0
	v_lshl_or_b32 v3, v4, 6, v3
	s_add_i32 s66, 0, 0x10000
	s_add_i32 s67, 0, 0x14000
	v_or_b32_e32 v152, 16, v150
	v_or_b32_e32 v153, 32, v150
	v_or_b32_e32 v154, 48, v150
	s_ashr_i32 s64, s38, 31
	s_mov_b32 s65, s38
	v_mov_b32_e32 v141, v139
	v_lshl_add_u32 v142, v13, 1, v3
	v_mov_b32_e32 v143, v139
	v_mov_b64_e32 v[144:145], 0xb00
	v_mov_b64_e32 v[146:147], 0xaff
	v_add_u32_e32 v155, s66, v151
	v_add_u32_e32 v156, s67, v151
	v_add_u32_e32 v157, 0, v5
	v_mov_b32_e32 v158, 0x358637bd
	s_movk_i32 s68, 0x1600
	v_lshlrev_b32_e32 v138, 1, v2
	s_add_u32 s98, s48, 0x40080
	s_addc_u32 s99, s49, 0
	v_lshl_add_u64 v[148:149], s[98:99], 0, v[140:141]
	s_add_i32 m0, s57, 0xc000
	s_nop 0
	global_load_lds_dwordx4 v[148:149], off
	v_lshl_add_u64 v[148:149], s[98:99], 0, v[142:143]
	s_add_i32 m0, s57, 0xe000
	s_nop 0
	global_load_lds_dwordx4 v[148:149], off
	s_waitcnt vmcnt(0)
	s_barrier
	s_branch .LBB0_837

.LBB0_839:
	s_ashr_i32 s27, s26, 31
	s_lshl_b64 s[42:43], s[26:27], 19
	s_add_u32 s42, s3, s42
	s_addc_u32 s43, s23, s43
	s_and_b64 s[44:45], s[4:5], exec
	s_cselect_b32 s27, s43, s49
	s_cselect_b32 s69, s42, s48
	s_ashr_i32 s25, s24, 31
	s_lshl_b64 s[44:45], s[24:25], 19
	s_add_u32 s44, s29, s44
	s_addc_u32 s45, s31, s45
	s_and_b64 s[52:53], s[4:5], exec
	s_cselect_b32 s25, s45, s51
	s_cselect_b32 s70, s44, s50
	s_add_u32 s48, s48, 0x40080
	s_addc_u32 s49, s49, 0
	s_add_u32 s71, s50, 0x100
	v_mov_b32_e32 v2, 0
	s_addc_u32 s72, s51, 0
	s_mov_b32 s73, -2
	v_mov_b32_e32 v3, v2
	v_mov_b32_e32 v4, v2
	v_mov_b32_e32 v5, v2
	v_mov_b32_e32 v14, v2
	v_mov_b32_e32 v15, v2
	v_mov_b32_e32 v16, v2
	v_mov_b32_e32 v17, v2
	v_mov_b32_e32 v22, v2
	v_mov_b32_e32 v23, v2
	v_mov_b32_e32 v24, v2
	v_mov_b32_e32 v25, v2
	v_mov_b32_e32 v30, v2
	v_mov_b32_e32 v31, v2
	v_mov_b32_e32 v32, v2
	v_mov_b32_e32 v33, v2
	v_mov_b32_e32 v38, v2
	v_mov_b32_e32 v39, v2
	v_mov_b32_e32 v40, v2
	v_mov_b32_e32 v41, v2
	v_mov_b32_e32 v46, v2
	v_mov_b32_e32 v47, v2
	v_mov_b32_e32 v48, v2
	v_mov_b32_e32 v49, v2
	v_mov_b32_e32 v54, v2
	v_mov_b32_e32 v55, v2
	v_mov_b32_e32 v56, v2
	v_mov_b32_e32 v57, v2
	v_mov_b32_e32 v62, v2
	v_mov_b32_e32 v63, v2
	v_mov_b32_e32 v64, v2
	v_mov_b32_e32 v65, v2
	v_mov_b32_e32 v6, v2
	v_mov_b32_e32 v7, v2
	v_mov_b32_e32 v8, v2
	v_mov_b32_e32 v9, v2
	v_mov_b32_e32 v10, v2
	v_mov_b32_e32 v11, v2
	v_mov_b32_e32 v12, v2
	v_mov_b32_e32 v13, v2
	v_mov_b32_e32 v18, v2
	v_mov_b32_e32 v19, v2
	v_mov_b32_e32 v20, v2
	v_mov_b32_e32 v21, v2
	v_mov_b32_e32 v26, v2
	v_mov_b32_e32 v27, v2
	v_mov_b32_e32 v28, v2
	v_mov_b32_e32 v29, v2
	v_mov_b32_e32 v34, v2
	v_mov_b32_e32 v35, v2
	v_mov_b32_e32 v36, v2
	v_mov_b32_e32 v37, v2
	v_mov_b32_e32 v42, v2
	v_mov_b32_e32 v43, v2
	v_mov_b32_e32 v44, v2
	v_mov_b32_e32 v45, v2
	v_mov_b32_e32 v50, v2
	v_mov_b32_e32 v51, v2
	v_mov_b32_e32 v52, v2
	v_mov_b32_e32 v53, v2
	v_mov_b32_e32 v58, v2
	v_mov_b32_e32 v59, v2
	v_mov_b32_e32 v60, v2
	v_mov_b32_e32 v61, v2
	v_mov_b32_e32 v70, v2
	v_mov_b32_e32 v71, v2
	v_mov_b32_e32 v72, v2
	v_mov_b32_e32 v73, v2
	v_mov_b32_e32 v78, v2
	v_mov_b32_e32 v79, v2
	v_mov_b32_e32 v80, v2
	v_mov_b32_e32 v81, v2
	s_waitcnt vmcnt(0)
	v_mov_b32_e32 v86, v2
	v_mov_b32_e32 v87, v2
	v_mov_b32_e32 v88, v2
	v_mov_b32_e32 v89, v2
	v_mov_b32_e32 v94, v2
	v_mov_b32_e32 v95, v2
	v_mov_b32_e32 v96, v2
	v_mov_b32_e32 v97, v2
	v_mov_b32_e32 v102, v2
	v_mov_b32_e32 v103, v2
	v_mov_b32_e32 v104, v2
	v_mov_b32_e32 v105, v2
	v_mov_b32_e32 v110, v2
	v_mov_b32_e32 v111, v2
	v_mov_b32_e32 v112, v2
	v_mov_b32_e32 v113, v2
	v_mov_b32_e32 v122, v2
	v_mov_b32_e32 v123, v2
	v_mov_b32_e32 v124, v2
	v_mov_b32_e32 v125, v2
	v_mov_b32_e32 v126, v2
	v_mov_b32_e32 v127, v2
	v_mov_b32_e32 v128, v2
	v_mov_b32_e32 v129, v2
	v_mov_b32_e32 v66, v2
	v_mov_b32_e32 v67, v2
	v_mov_b32_e32 v68, v2
	v_mov_b32_e32 v69, v2
	v_mov_b32_e32 v74, v2
	v_mov_b32_e32 v75, v2
	v_mov_b32_e32 v76, v2
	v_mov_b32_e32 v77, v2
	v_mov_b32_e32 v82, v2
	v_mov_b32_e32 v83, v2
	v_mov_b32_e32 v84, v2
	v_mov_b32_e32 v85, v2
	v_mov_b32_e32 v90, v2
	v_mov_b32_e32 v91, v2
	v_mov_b32_e32 v92, v2
	v_mov_b32_e32 v93, v2
	v_mov_b32_e32 v98, v2
	v_mov_b32_e32 v99, v2
	v_mov_b32_e32 v100, v2
	v_mov_b32_e32 v101, v2
	v_mov_b32_e32 v106, v2
	v_mov_b32_e32 v107, v2
	v_mov_b32_e32 v108, v2
	v_mov_b32_e32 v109, v2
	v_mov_b32_e32 v114, v2
	v_mov_b32_e32 v115, v2
	v_mov_b32_e32 v116, v2
	v_mov_b32_e32 v117, v2
	v_mov_b32_e32 v118, v2
	v_mov_b32_e32 v119, v2
	v_mov_b32_e32 v120, v2
	v_mov_b32_e32 v121, v2
	v_add_u32_e32 v159, 0x18000, v151
	v_add_u32_e32 v239, 0x1c000, v151
	ds_read_b128 v[160:163], v155
	ds_read_b128 v[164:167], v155 offset:1024
	ds_read_b128 v[168:171], v155 offset:2048
	ds_read_b128 v[172:175], v155 offset:3072
	ds_read_b128 v[176:179], v156
	ds_read_b128 v[180:183], v156 offset:1024
	ds_read_b128 v[184:187], v156 offset:2048
	ds_read_b128 v[188:191], v156 offset:3072
	ds_read_b128 v[192:195], v157
	ds_read_b128 v[196:199], v157 offset:1024
	ds_read_b128 v[200:203], v157 offset:2048
	ds_read_b128 v[204:207], v157 offset:3072
	ds_read_b128 v[208:211], v157 offset:4096
	ds_read_b128 v[212:215], v157 offset:5120
	ds_read_b128 v[216:219], v157 offset:6144
	ds_read_b128 v[220:223], v157 offset:7168
	s_waitcnt lgkmcnt(7)
	v_mfma_f32_16x16x32_bf16 v[118:121], v[160:163], v[192:195], v[118:121]
	v_mfma_f32_16x16x32_bf16 v[114:117], v[168:171], v[192:195], v[114:117]
	v_mfma_f32_16x16x32_bf16 v[126:129], v[176:179], v[192:195], v[126:129]
	v_mfma_f32_16x16x32_bf16 v[122:125], v[184:187], v[192:195], v[122:125]
	s_waitcnt lgkmcnt(5)
	v_mfma_f32_16x16x32_bf16 v[106:109], v[160:163], v[200:203], v[106:109]
	v_mfma_f32_16x16x32_bf16 v[98:101], v[168:171], v[200:203], v[98:101]
	v_mfma_f32_16x16x32_bf16 v[110:113], v[176:179], v[200:203], v[110:113]
	v_mfma_f32_16x16x32_bf16 v[102:105], v[184:187], v[200:203], v[102:105]
	ds_read_b128 v[192:195], v157 offset:16384
	s_waitcnt lgkmcnt(4)
	v_mfma_f32_16x16x32_bf16 v[90:93], v[160:163], v[208:211], v[90:93]
	v_mfma_f32_16x16x32_bf16 v[82:85], v[168:171], v[208:211], v[82:85]
	v_mfma_f32_16x16x32_bf16 v[94:97], v[176:179], v[208:211], v[94:97]
	v_mfma_f32_16x16x32_bf16 v[86:89], v[184:187], v[208:211], v[86:89]
	ds_read_b128 v[200:203], v157 offset:18432
	s_waitcnt lgkmcnt(3)
	v_mfma_f32_16x16x32_bf16 v[74:77], v[160:163], v[216:219], v[74:77]
	v_mfma_f32_16x16x32_bf16 v[66:69], v[168:171], v[216:219], v[66:69]
	v_mfma_f32_16x16x32_bf16 v[78:81], v[176:179], v[216:219], v[78:81]
	v_mfma_f32_16x16x32_bf16 v[70:73], v[184:187], v[216:219], v[70:73]
	ds_read_b128 v[208:211], v157 offset:20480
	s_waitcnt lgkmcnt(9)
	v_mfma_f32_16x16x32_bf16 v[118:121], v[164:167], v[196:199], v[118:121]
	v_mfma_f32_16x16x32_bf16 v[114:117], v[172:175], v[196:199], v[114:117]
	v_mfma_f32_16x16x32_bf16 v[126:129], v[180:183], v[196:199], v[126:129]
	v_mfma_f32_16x16x32_bf16 v[122:125], v[188:191], v[196:199], v[122:125]
	ds_read_b128 v[216:219], v157 offset:22528
	s_waitcnt lgkmcnt(8)
	v_mfma_f32_16x16x32_bf16 v[106:109], v[164:167], v[204:207], v[106:109]
	v_mfma_f32_16x16x32_bf16 v[98:101], v[172:175], v[204:207], v[98:101]
	v_mfma_f32_16x16x32_bf16 v[110:113], v[180:183], v[204:207], v[110:113]
	v_mfma_f32_16x16x32_bf16 v[102:105], v[188:191], v[204:207], v[102:105]
	ds_read_b128 v[196:199], v157 offset:17408
	s_waitcnt lgkmcnt(7)
	v_mfma_f32_16x16x32_bf16 v[90:93], v[164:167], v[212:215], v[90:93]
	v_mfma_f32_16x16x32_bf16 v[82:85], v[172:175], v[212:215], v[82:85]
	v_mfma_f32_16x16x32_bf16 v[94:97], v[180:183], v[212:215], v[94:97]
	v_mfma_f32_16x16x32_bf16 v[86:89], v[188:191], v[212:215], v[86:89]
	ds_read_b128 v[204:207], v157 offset:19456
	s_waitcnt lgkmcnt(6)
	v_mfma_f32_16x16x32_bf16 v[74:77], v[164:167], v[220:223], v[74:77]
	v_mfma_f32_16x16x32_bf16 v[66:69], v[172:175], v[220:223], v[66:69]
	v_mfma_f32_16x16x32_bf16 v[78:81], v[180:183], v[220:223], v[78:81]
	v_mfma_f32_16x16x32_bf16 v[70:73], v[188:191], v[220:223], v[70:73]
	ds_read_b128 v[212:215], v157 offset:21504

.Lswp_s23_p6:
	s_lshl_b32 s25, s46, 8
	v_add_u32_e32 v148, s25, v150
	v_ashrrev_i32_e32 v149, 31, v148
	v_lshl_add_u64 v[160:161], v[148:149], 2, s[10:11]
	global_load_dword v149, v[160:161], off
	global_load_dword v232, v[160:161], off offset:64
	global_load_dword v233, v[160:161], off offset:128
	global_load_dword v234, v[160:161], off offset:192
	global_load_dword v235, v[160:161], off offset:512
	global_load_dword v236, v[160:161], off offset:576
	global_load_dword v237, v[160:161], off offset:640
	global_load_dword v238, v[160:161], off offset:704
	s_and_b64 vcc, exec, s[16:17]
	s_cbranch_vccz .LBB0_843
.LBB0_843:
	v_pk_mul_f32 v[128:129], v[120:121], v[128:129]
	v_pk_mul_f32 v[126:127], v[118:119], v[126:127]
	v_pk_mul_f32 v[124:125], v[116:117], v[124:125]
	v_pk_mul_f32 v[160:161], v[114:115], v[122:123]
	v_add_u32_e32 v162, s25, v152
	s_lshl_b32 s46, s47, 7
	v_mov_b64_e32 v[122:123], s[12:13]
	s_ashr_i32 s47, s46, 31
	v_mad_i64_i32 v[164:165], s[48:49], v148, s68, v[122:123]
	s_lshl_b64 s[46:47], s[46:47], 1
	v_lshl_add_u64 v[164:165], v[164:165], 0, s[46:47]
	v_lshl_add_u64 v[164:165], v[164:165], 0, v[138:139]
	v_pk_mul_f32 v[112:113], v[108:109], v[112:113]
	v_pk_mul_f32 v[110:111], v[106:107], v[110:111]
	v_pk_mul_f32 v[104:105], v[100:101], v[104:105]
	v_pk_mul_f32 v[102:103], v[98:99], v[102:103]
	v_pk_mul_f32 v[96:97], v[92:93], v[96:97]
	v_pk_mul_f32 v[94:95], v[90:91], v[94:95]
	v_pk_mul_f32 v[88:89], v[84:85], v[88:89]
	v_pk_mul_f32 v[86:87], v[82:83], v[86:87]
	v_pk_mul_f32 v[80:81], v[76:77], v[80:81]
	v_pk_mul_f32 v[78:79], v[74:75], v[78:79]
	v_pk_mul_f32 v[72:73], v[68:69], v[72:73]
	v_pk_mul_f32 v[70:71], v[66:67], v[70:71]
	v_pk_mul_f32 v[64:65], v[60:61], v[64:65]
	v_pk_mul_f32 v[62:63], v[58:59], v[62:63]
	v_pk_mul_f32 v[56:57], v[52:53], v[56:57]
	v_pk_mul_f32 v[54:55], v[50:51], v[54:55]
	v_pk_mul_f32 v[48:49], v[44:45], v[48:49]
	v_pk_mul_f32 v[46:47], v[42:43], v[46:47]
	v_pk_mul_f32 v[40:41], v[36:37], v[40:41]
	v_pk_mul_f32 v[38:39], v[34:35], v[38:39]
	v_pk_mul_f32 v[32:33], v[28:29], v[32:33]
	v_pk_mul_f32 v[30:31], v[26:27], v[30:31]
	v_pk_mul_f32 v[24:25], v[20:21], v[24:25]
	v_pk_mul_f32 v[22:23], v[18:19], v[22:23]
	v_pk_mul_f32 v[16:17], v[12:13], v[16:17]
	v_pk_mul_f32 v[14:15], v[10:11], v[14:15]
	v_pk_mul_f32 v[4:5], v[8:9], v[4:5]
	v_pk_mul_f32 v[2:3], v[6:7], v[2:3]
	s_andn2_b64 vcc, exec, s[4:5]
	s_waitcnt vmcnt(0)
	v_fmamk_f32 v149, v149, 0x3a800000, v158
	v_rsq_f32_e32 v149, v149
	s_nop 0
	v_mul_f32_e32 v168, 0xbfb8aa3b, v149
	v_pk_mul_f32 v[120:121], v[120:121], v[168:169] op_sel_hi:[1,0]
	v_pk_mul_f32 v[118:119], v[118:119], v[168:169] op_sel_hi:[1,0]
	v_pk_mul_f32 v[116:117], v[116:117], v[168:169] op_sel_hi:[1,0]
	v_pk_mul_f32 v[114:115], v[114:115], v[168:169] op_sel_hi:[1,0]
	v_exp_f32_e32 v118, v118
	v_exp_f32_e32 v119, v119
	v_exp_f32_e32 v120, v120
	v_exp_f32_e32 v121, v121
	v_exp_f32_e32 v114, v114
	v_exp_f32_e32 v115, v115
	v_exp_f32_e32 v116, v116
	v_exp_f32_e32 v117, v117
	v_mul_f32_e32 v170, v149, v149
	v_add_f32_e32 v118, 1.0, v118
	v_add_f32_e32 v119, 1.0, v119
	v_add_f32_e32 v120, 1.0, v120
	v_add_f32_e32 v121, 1.0, v121
	v_add_f32_e32 v149, 1.0, v114
	v_add_f32_e32 v159, 1.0, v115
	v_add_f32_e32 v163, 1.0, v116
	v_add_f32_e32 v168, 1.0, v117
	v_rcp_f32_e32 v114, v118
	v_rcp_f32_e32 v115, v119
	v_rcp_f32_e32 v116, v120
	v_rcp_f32_e32 v117, v121
	v_rcp_f32_e32 v118, v149
	v_rcp_f32_e32 v119, v159
	v_rcp_f32_e32 v120, v163
	v_rcp_f32_e32 v121, v168
	v_pk_mul_f32 v[114:115], v[170:171], v[114:115] op_sel_hi:[0,1]
	v_pk_mul_f32 v[116:117], v[170:171], v[116:117] op_sel_hi:[0,1]
	v_pk_mul_f32 v[118:119], v[170:171], v[118:119] op_sel_hi:[0,1]
	v_pk_mul_f32 v[120:121], v[170:171], v[120:121] op_sel_hi:[0,1]
	v_pk_mul_f32 v[116:117], v[128:129], v[116:117]
	v_pk_mul_f32 v[114:115], v[126:127], v[114:115]
	v_pk_mul_f32 v[120:121], v[124:125], v[120:121]
	v_pk_mul_f32 v[118:119], v[160:161], v[118:119]
	v_cvt_pk_bf16_f32 v114, v114, v115
	v_cvt_pk_bf16_f32 v115, v116, v117
	v_cvt_pk_bf16_f32 v116, v118, v119
	v_cvt_pk_bf16_f32 v117, v120, v121
	global_store_dwordx4 v[164:165], v[114:117], off
	v_fmamk_f32 v118, v232, 0x3a800000, v158
	v_rsq_f32_e32 v121, v118
	v_add_u32_e32 v114, s25, v153
	v_mul_f32_e32 v120, 0xbfb8aa3b, v121
	v_pk_mul_f32 v[108:109], v[108:109], v[120:121] op_sel_hi:[1,0]
	v_pk_mul_f32 v[106:107], v[106:107], v[120:121] op_sel_hi:[1,0]
	v_pk_mul_f32 v[100:101], v[100:101], v[120:121] op_sel_hi:[1,0]
	v_pk_mul_f32 v[98:99], v[98:99], v[120:121] op_sel_hi:[1,0]
	v_exp_f32_e32 v106, v106
	v_exp_f32_e32 v107, v107
	v_exp_f32_e32 v108, v108
	v_exp_f32_e32 v109, v109
	v_exp_f32_e32 v98, v98
	v_exp_f32_e32 v99, v99
	v_exp_f32_e32 v100, v100
	v_exp_f32_e32 v101, v101
	v_mul_f32_e32 v124, v121, v121
	v_add_f32_e32 v106, 1.0, v106
	v_add_f32_e32 v107, 1.0, v107
	v_add_f32_e32 v108, 1.0, v108
	v_add_f32_e32 v109, 1.0, v109
	v_add_f32_e32 v115, 1.0, v98
	v_add_f32_e32 v120, 1.0, v99
	v_add_f32_e32 v121, 1.0, v100
	v_add_f32_e32 v125, 1.0, v101
	v_rcp_f32_e32 v98, v106
	v_rcp_f32_e32 v99, v107
	v_rcp_f32_e32 v100, v108
	v_rcp_f32_e32 v101, v109
	v_rcp_f32_e32 v106, v115
	v_rcp_f32_e32 v107, v120
	v_rcp_f32_e32 v108, v121
	v_rcp_f32_e32 v109, v125
	v_mad_i64_i32 v[116:117], s[48:49], v162, s68, v[122:123]
	v_pk_mul_f32 v[98:99], v[124:125], v[98:99] op_sel_hi:[0,1]
	v_pk_mul_f32 v[100:101], v[124:125], v[100:101] op_sel_hi:[0,1]
	v_pk_mul_f32 v[106:107], v[124:125], v[106:107] op_sel_hi:[0,1]
	v_pk_mul_f32 v[108:109], v[124:125], v[108:109] op_sel_hi:[0,1]
	v_lshl_add_u64 v[116:117], v[116:117], 0, s[46:47]
	v_pk_mul_f32 v[100:101], v[112:113], v[100:101]
	v_pk_mul_f32 v[98:99], v[110:111], v[98:99]
	v_pk_mul_f32 v[104:105], v[104:105], v[108:109]
	v_pk_mul_f32 v[102:103], v[102:103], v[106:107]
	v_lshl_add_u64 v[116:117], v[116:117], 0, v[138:139]
	v_cvt_pk_bf16_f32 v98, v98, v99
	v_cvt_pk_bf16_f32 v99, v100, v101
	v_cvt_pk_bf16_f32 v100, v102, v103
	v_cvt_pk_bf16_f32 v101, v104, v105
	global_store_dwordx4 v[116:117], v[98:101], off
	v_fmamk_f32 v102, v233, 0x3a800000, v158
	v_rsq_f32_e32 v105, v102
	v_add_u32_e32 v98, s25, v154
	v_mul_f32_e32 v104, 0xbfb8aa3b, v105
	v_pk_mul_f32 v[92:93], v[92:93], v[104:105] op_sel_hi:[1,0]
	v_pk_mul_f32 v[90:91], v[90:91], v[104:105] op_sel_hi:[1,0]
	v_pk_mul_f32 v[84:85], v[84:85], v[104:105] op_sel_hi:[1,0]
	v_pk_mul_f32 v[82:83], v[82:83], v[104:105] op_sel_hi:[1,0]
	v_exp_f32_e32 v90, v90
	v_exp_f32_e32 v91, v91
	v_exp_f32_e32 v92, v92
	v_exp_f32_e32 v93, v93
	v_exp_f32_e32 v82, v82
	v_exp_f32_e32 v83, v83
	v_exp_f32_e32 v84, v84
	v_exp_f32_e32 v85, v85
	v_mul_f32_e32 v106, v105, v105
	v_add_f32_e32 v90, 1.0, v90
	v_add_f32_e32 v91, 1.0, v91
	v_add_f32_e32 v92, 1.0, v92
	v_add_f32_e32 v93, 1.0, v93
	v_add_f32_e32 v99, 1.0, v82
	v_add_f32_e32 v104, 1.0, v83
	v_add_f32_e32 v105, 1.0, v84
	v_add_f32_e32 v107, 1.0, v85
	v_rcp_f32_e32 v82, v90
	v_rcp_f32_e32 v83, v91
	v_rcp_f32_e32 v84, v92
	v_rcp_f32_e32 v85, v93
	v_rcp_f32_e32 v90, v99
	v_rcp_f32_e32 v91, v104
	v_rcp_f32_e32 v92, v105
	v_rcp_f32_e32 v93, v107
	v_mad_i64_i32 v[100:101], s[48:49], v114, s68, v[122:123]
	v_pk_mul_f32 v[82:83], v[106:107], v[82:83] op_sel_hi:[0,1]
	v_pk_mul_f32 v[84:85], v[106:107], v[84:85] op_sel_hi:[0,1]
	v_pk_mul_f32 v[90:91], v[106:107], v[90:91] op_sel_hi:[0,1]
	v_pk_mul_f32 v[92:93], v[106:107], v[92:93] op_sel_hi:[0,1]
	v_lshl_add_u64 v[100:101], v[100:101], 0, s[46:47]
	v_pk_mul_f32 v[84:85], v[96:97], v[84:85]
	v_pk_mul_f32 v[82:83], v[94:95], v[82:83]
	v_pk_mul_f32 v[88:89], v[88:89], v[92:93]
	v_pk_mul_f32 v[86:87], v[86:87], v[90:91]
	v_lshl_add_u64 v[100:101], v[100:101], 0, v[138:139]
	v_cvt_pk_bf16_f32 v82, v82, v83
	v_cvt_pk_bf16_f32 v83, v84, v85
	v_cvt_pk_bf16_f32 v84, v86, v87
	v_cvt_pk_bf16_f32 v85, v88, v89
	global_store_dwordx4 v[100:101], v[82:85], off
	s_nop 0
	s_nop 0
	v_add_u32_e32 v84, 0x80, v148
	v_mad_i64_i32 v[82:83], s[48:49], v98, s68, v[122:123]
	v_lshl_add_u64 v[82:83], v[82:83], 0, s[46:47]
	v_lshl_add_u64 v[82:83], v[82:83], 0, v[138:139]
	v_fmamk_f32 v85, v234, 0x3a800000, v158
	v_rsq_f32_e32 v89, v85
	s_nop 0
	v_mul_f32_e32 v88, 0xbfb8aa3b, v89
	v_pk_mul_f32 v[76:77], v[76:77], v[88:89] op_sel_hi:[1,0]
	v_pk_mul_f32 v[74:75], v[74:75], v[88:89] op_sel_hi:[1,0]
	v_pk_mul_f32 v[68:69], v[68:69], v[88:89] op_sel_hi:[1,0]
	v_pk_mul_f32 v[66:67], v[66:67], v[88:89] op_sel_hi:[1,0]
	v_exp_f32_e32 v74, v74
	v_exp_f32_e32 v75, v75
	v_exp_f32_e32 v76, v76
	v_exp_f32_e32 v77, v77
	v_exp_f32_e32 v66, v66
	v_exp_f32_e32 v67, v67
	v_exp_f32_e32 v68, v68
	v_exp_f32_e32 v69, v69
	v_mul_f32_e32 v90, v89, v89
	v_add_f32_e32 v74, 1.0, v74
	v_add_f32_e32 v75, 1.0, v75
	v_add_f32_e32 v76, 1.0, v76
	v_add_f32_e32 v77, 1.0, v77
	v_add_f32_e32 v85, 1.0, v66
	v_add_f32_e32 v88, 1.0, v67
	v_add_f32_e32 v89, 1.0, v68
	v_add_f32_e32 v91, 1.0, v69
	v_rcp_f32_e32 v66, v74
	v_rcp_f32_e32 v67, v75
	v_rcp_f32_e32 v68, v76
	v_rcp_f32_e32 v69, v77
	v_rcp_f32_e32 v74, v85
	v_rcp_f32_e32 v75, v88
	v_rcp_f32_e32 v76, v89
	v_rcp_f32_e32 v77, v91
	v_pk_mul_f32 v[66:67], v[90:91], v[66:67] op_sel_hi:[0,1]
	v_pk_mul_f32 v[68:69], v[90:91], v[68:69] op_sel_hi:[0,1]
	v_pk_mul_f32 v[74:75], v[90:91], v[74:75] op_sel_hi:[0,1]
	v_pk_mul_f32 v[76:77], v[90:91], v[76:77] op_sel_hi:[0,1]
	v_pk_mul_f32 v[68:69], v[80:81], v[68:69]
	v_pk_mul_f32 v[66:67], v[78:79], v[66:67]
	v_pk_mul_f32 v[72:73], v[72:73], v[76:77]
	v_pk_mul_f32 v[70:71], v[70:71], v[74:75]
	v_cvt_pk_bf16_f32 v66, v66, v67
	v_cvt_pk_bf16_f32 v67, v68, v69
	v_cvt_pk_bf16_f32 v68, v70, v71
	v_cvt_pk_bf16_f32 v69, v72, v73
	global_store_dwordx4 v[82:83], v[66:69], off
	v_fmamk_f32 v70, v235, 0x3a800000, v158
	v_rsq_f32_e32 v73, v70
	v_add_u32_e32 v66, 0x90, v148
	v_mul_f32_e32 v72, 0xbfb8aa3b, v73
	v_pk_mul_f32 v[60:61], v[60:61], v[72:73] op_sel_hi:[1,0]
	v_pk_mul_f32 v[58:59], v[58:59], v[72:73] op_sel_hi:[1,0]
	v_pk_mul_f32 v[52:53], v[52:53], v[72:73] op_sel_hi:[1,0]
	v_pk_mul_f32 v[50:51], v[50:51], v[72:73] op_sel_hi:[1,0]
	v_exp_f32_e32 v58, v58
	v_exp_f32_e32 v59, v59
	v_exp_f32_e32 v60, v60
	v_exp_f32_e32 v61, v61
	v_exp_f32_e32 v50, v50
	v_exp_f32_e32 v51, v51
	v_exp_f32_e32 v52, v52
	v_exp_f32_e32 v53, v53
	v_mul_f32_e32 v74, v73, v73
	v_add_f32_e32 v58, 1.0, v58
	v_add_f32_e32 v59, 1.0, v59
	v_add_f32_e32 v60, 1.0, v60
	v_add_f32_e32 v61, 1.0, v61
	v_add_f32_e32 v67, 1.0, v50
	v_add_f32_e32 v72, 1.0, v51
	v_add_f32_e32 v73, 1.0, v52
	v_add_f32_e32 v75, 1.0, v53
	v_rcp_f32_e32 v50, v58
	v_rcp_f32_e32 v51, v59
	v_rcp_f32_e32 v52, v60
	v_rcp_f32_e32 v53, v61
	v_rcp_f32_e32 v58, v67
	v_rcp_f32_e32 v59, v72
	v_rcp_f32_e32 v60, v73
	v_rcp_f32_e32 v61, v75
	v_mad_i64_i32 v[68:69], s[48:49], v84, s68, v[122:123]
	v_pk_mul_f32 v[50:51], v[74:75], v[50:51] op_sel_hi:[0,1]
	v_pk_mul_f32 v[52:53], v[74:75], v[52:53] op_sel_hi:[0,1]
	v_pk_mul_f32 v[58:59], v[74:75], v[58:59] op_sel_hi:[0,1]
	v_pk_mul_f32 v[60:61], v[74:75], v[60:61] op_sel_hi:[0,1]
	v_lshl_add_u64 v[68:69], v[68:69], 0, s[46:47]
	v_pk_mul_f32 v[52:53], v[64:65], v[52:53]
	v_pk_mul_f32 v[50:51], v[62:63], v[50:51]
	v_pk_mul_f32 v[56:57], v[56:57], v[60:61]
	v_pk_mul_f32 v[54:55], v[54:55], v[58:59]
	v_lshl_add_u64 v[68:69], v[68:69], 0, v[138:139]
	v_cvt_pk_bf16_f32 v50, v50, v51
	v_cvt_pk_bf16_f32 v51, v52, v53
	v_cvt_pk_bf16_f32 v52, v54, v55
	v_cvt_pk_bf16_f32 v53, v56, v57
	global_store_dwordx4 v[68:69], v[50:53], off
	v_fmamk_f32 v54, v236, 0x3a800000, v158
	v_rsq_f32_e32 v57, v54
	v_add_u32_e32 v50, 0xa0, v148
	v_mul_f32_e32 v56, 0xbfb8aa3b, v57
	v_pk_mul_f32 v[44:45], v[44:45], v[56:57] op_sel_hi:[1,0]
	v_pk_mul_f32 v[42:43], v[42:43], v[56:57] op_sel_hi:[1,0]
	v_pk_mul_f32 v[36:37], v[36:37], v[56:57] op_sel_hi:[1,0]
	v_pk_mul_f32 v[34:35], v[34:35], v[56:57] op_sel_hi:[1,0]
	v_exp_f32_e32 v42, v42
	v_exp_f32_e32 v43, v43
	v_exp_f32_e32 v44, v44
	v_exp_f32_e32 v45, v45
	v_exp_f32_e32 v34, v34
	v_exp_f32_e32 v35, v35
	v_exp_f32_e32 v36, v36
	v_exp_f32_e32 v37, v37
	v_mul_f32_e32 v58, v57, v57
	v_add_f32_e32 v42, 1.0, v42
	v_add_f32_e32 v43, 1.0, v43
	v_add_f32_e32 v44, 1.0, v44
	v_add_f32_e32 v45, 1.0, v45
	v_add_f32_e32 v51, 1.0, v34
	v_add_f32_e32 v56, 1.0, v35
	v_add_f32_e32 v57, 1.0, v36
	v_add_f32_e32 v59, 1.0, v37
	v_rcp_f32_e32 v34, v42
	v_rcp_f32_e32 v35, v43
	v_rcp_f32_e32 v36, v44
	v_rcp_f32_e32 v37, v45
	v_rcp_f32_e32 v42, v51
	v_rcp_f32_e32 v43, v56
	v_rcp_f32_e32 v44, v57
	v_rcp_f32_e32 v45, v59
	v_mad_i64_i32 v[52:53], s[48:49], v66, s68, v[122:123]
	v_pk_mul_f32 v[34:35], v[58:59], v[34:35] op_sel_hi:[0,1]
	v_pk_mul_f32 v[36:37], v[58:59], v[36:37] op_sel_hi:[0,1]
	v_pk_mul_f32 v[42:43], v[58:59], v[42:43] op_sel_hi:[0,1]
	v_pk_mul_f32 v[44:45], v[58:59], v[44:45] op_sel_hi:[0,1]
	v_lshl_add_u64 v[52:53], v[52:53], 0, s[46:47]
	v_pk_mul_f32 v[36:37], v[48:49], v[36:37]
	v_pk_mul_f32 v[34:35], v[46:47], v[34:35]
	v_pk_mul_f32 v[40:41], v[40:41], v[44:45]
	v_pk_mul_f32 v[38:39], v[38:39], v[42:43]
	v_lshl_add_u64 v[52:53], v[52:53], 0, v[138:139]
	v_cvt_pk_bf16_f32 v34, v34, v35
	v_cvt_pk_bf16_f32 v35, v36, v37
	v_cvt_pk_bf16_f32 v36, v38, v39
	v_cvt_pk_bf16_f32 v37, v40, v41
	global_store_dwordx4 v[52:53], v[34:37], off
	v_fmamk_f32 v38, v237, 0x3a800000, v158
	v_rsq_f32_e32 v41, v38
	v_add_u32_e32 v34, 0xb0, v148
	v_mul_f32_e32 v40, 0xbfb8aa3b, v41
	v_pk_mul_f32 v[28:29], v[28:29], v[40:41] op_sel_hi:[1,0]
	v_pk_mul_f32 v[26:27], v[26:27], v[40:41] op_sel_hi:[1,0]
	v_pk_mul_f32 v[20:21], v[20:21], v[40:41] op_sel_hi:[1,0]
	v_pk_mul_f32 v[18:19], v[18:19], v[40:41] op_sel_hi:[1,0]
	v_exp_f32_e32 v26, v26
	v_exp_f32_e32 v27, v27
	v_exp_f32_e32 v28, v28
	v_exp_f32_e32 v29, v29
	v_exp_f32_e32 v18, v18
	v_exp_f32_e32 v19, v19
	v_exp_f32_e32 v20, v20
	v_exp_f32_e32 v21, v21
	v_mul_f32_e32 v42, v41, v41
	v_add_f32_e32 v26, 1.0, v26
	v_add_f32_e32 v27, 1.0, v27
	v_add_f32_e32 v28, 1.0, v28
	v_add_f32_e32 v29, 1.0, v29
	v_add_f32_e32 v35, 1.0, v18
	v_add_f32_e32 v40, 1.0, v19
	v_add_f32_e32 v41, 1.0, v20
	v_add_f32_e32 v43, 1.0, v21
	v_rcp_f32_e32 v18, v26
	v_rcp_f32_e32 v19, v27
	v_rcp_f32_e32 v20, v28
	v_rcp_f32_e32 v21, v29
	v_rcp_f32_e32 v26, v35
	v_rcp_f32_e32 v27, v40
	v_rcp_f32_e32 v28, v41
	v_rcp_f32_e32 v29, v43
	v_mad_i64_i32 v[36:37], s[48:49], v50, s68, v[122:123]
	v_pk_mul_f32 v[18:19], v[42:43], v[18:19] op_sel_hi:[0,1]
	v_pk_mul_f32 v[20:21], v[42:43], v[20:21] op_sel_hi:[0,1]
	v_pk_mul_f32 v[26:27], v[42:43], v[26:27] op_sel_hi:[0,1]
	v_pk_mul_f32 v[28:29], v[42:43], v[28:29] op_sel_hi:[0,1]
	v_lshl_add_u64 v[36:37], v[36:37], 0, s[46:47]
	v_pk_mul_f32 v[20:21], v[32:33], v[20:21]
	v_pk_mul_f32 v[18:19], v[30:31], v[18:19]
	v_pk_mul_f32 v[24:25], v[24:25], v[28:29]
	v_pk_mul_f32 v[22:23], v[22:23], v[26:27]
	v_lshl_add_u64 v[36:37], v[36:37], 0, v[138:139]
	v_cvt_pk_bf16_f32 v18, v18, v19
	v_cvt_pk_bf16_f32 v19, v20, v21
	v_cvt_pk_bf16_f32 v20, v22, v23
	v_cvt_pk_bf16_f32 v21, v24, v25
	global_store_dwordx4 v[36:37], v[18:21], off
	s_nop 0
	s_nop 0
	v_fmamk_f32 v18, v238, 0x3a800000, v158
	v_rsq_f32_e32 v21, v18
	v_mad_i64_i32 v[18:19], s[4:5], v34, s68, v[122:123]
	v_lshl_add_u64 v[18:19], v[18:19], 0, s[46:47]
	v_mul_f32_e32 v20, 0xbfb8aa3b, v21
	v_pk_mul_f32 v[12:13], v[12:13], v[20:21] op_sel_hi:[1,0]
	v_pk_mul_f32 v[10:11], v[10:11], v[20:21] op_sel_hi:[1,0]
	v_pk_mul_f32 v[8:9], v[8:9], v[20:21] op_sel_hi:[1,0]
	v_pk_mul_f32 v[6:7], v[6:7], v[20:21] op_sel_hi:[1,0]
	v_exp_f32_e32 v10, v10
	v_exp_f32_e32 v11, v11
	v_exp_f32_e32 v12, v12
	v_exp_f32_e32 v13, v13
	v_exp_f32_e32 v6, v6
	v_exp_f32_e32 v7, v7
	v_exp_f32_e32 v8, v8
	v_exp_f32_e32 v9, v9
	v_mul_f32_e32 v22, v21, v21
	v_add_f32_e32 v10, 1.0, v10
	v_add_f32_e32 v11, 1.0, v11
	v_add_f32_e32 v12, 1.0, v12
	v_add_f32_e32 v13, 1.0, v13
	v_add_f32_e32 v20, 1.0, v6
	v_add_f32_e32 v21, 1.0, v7
	v_add_f32_e32 v23, 1.0, v8
	v_add_f32_e32 v24, 1.0, v9
	v_rcp_f32_e32 v6, v10
	v_rcp_f32_e32 v7, v11
	v_rcp_f32_e32 v8, v12
	v_rcp_f32_e32 v9, v13
	v_rcp_f32_e32 v10, v20
	v_rcp_f32_e32 v11, v21
	v_rcp_f32_e32 v12, v23
	v_rcp_f32_e32 v13, v24
	v_pk_mul_f32 v[6:7], v[22:23], v[6:7] op_sel_hi:[0,1]
	v_pk_mul_f32 v[8:9], v[22:23], v[8:9] op_sel_hi:[0,1]
	v_pk_mul_f32 v[10:11], v[22:23], v[10:11] op_sel_hi:[0,1]
	v_pk_mul_f32 v[12:13], v[22:23], v[12:13] op_sel_hi:[0,1]
	v_pk_mul_f32 v[8:9], v[16:17], v[8:9]
	v_pk_mul_f32 v[6:7], v[14:15], v[6:7]
	v_pk_mul_f32 v[12:13], v[4:5], v[12:13]
	v_pk_mul_f32 v[4:5], v[2:3], v[10:11]
	v_lshl_add_u64 v[18:19], v[18:19], 0, v[138:139]
	v_cvt_pk_bf16_f32 v2, v6, v7
	v_cvt_pk_bf16_f32 v3, v8, v9
	v_cvt_pk_bf16_f32 v4, v4, v5
	v_cvt_pk_bf16_f32 v5, v12, v13
	s_mov_b64 s[4:5], -1
	global_store_dwordx4 v[18:19], v[2:5], off
	s_cbranch_vccnz .LBB0_836
	s_andn2_b64 vcc, exec, s[8:9]
	s_cbranch_vccnz .LBB0_835
	s_branch .LBB0_835

.LBB0_1124:
	s_waitcnt lgkmcnt(0)
	s_add_u32 s8, s8, 0x60000
	s_addc_u32 s9, s9, 0
	s_add_u32 s10, s4, 0xa400000
	s_addc_u32 s11, s5, 0
	s_lshl_b32 s4, s14, 5
	s_mov_b64 s[14:15], 0x80
	s_and_b32 s26, s4, 0x60
	s_add_i32 m0, s57, 0x18000
	v_lshl_add_u64 v[8:9], v[8:9], 0, s[14:15]
	s_lshl_b32 s25, s24, 13
	s_lshl_b32 s27, s26, 7
	s_waitcnt vmcnt(2)
	global_load_lds_dwordx4 v[8:9], off
	v_lshl_add_u64 v[6:7], v[6:7], 0, s[14:15]
	s_add_i32 m0, s57, 0x1a000
	s_add_i32 s62, s57, 0x8000
	s_add_i32 s63, s57, 0xa000
	global_load_lds_dwordx4 v[6:7], off
	v_lshl_add_u64 v[2:3], v[2:3], 0, s[14:15]
	s_mov_b32 m0, s62
	s_add_u32 s4, s50, 0x40080
	global_load_lds_dwordx4 v[2:3], off
	v_lshl_add_u64 v[2:3], v[4:5], 0, s[14:15]
	s_mov_b32 m0, s63
	s_addc_u32 s5, s51, 0
	global_load_lds_dwordx4 v[2:3], off
	s_add_i32 m0, s57, 0x1c000
	v_lshl_add_u64 v[2:3], s[4:5], 0, v[134:135]
	global_load_lds_dwordx4 v[2:3], off
	v_lshl_add_u64 v[2:3], s[4:5], 0, v[130:131]
	s_add_i32 m0, s57, 0x1e000
	s_cmpk_lt_u32 s17, 0x100
	global_load_lds_dwordx4 v[2:3], off
	v_lshrrev_b32_e32 v3, 1, v10
	v_and_b32_e32 v3, 24, v3
	v_and_b32_e32 v2, 15, v10
	v_lshlrev_b32_e32 v4, 1, v3
	v_lshl_or_b32 v150, s24, 6, v2
	v_lshl_or_b32 v2, v2, 6, v4
	v_lshlrev_b32_e32 v4, 2, v10
	v_and_b32_e32 v4, 32, v4
	v_bitop3_b32 v5, v2, s25, v4 bitop3:0xde
	v_bitop3_b32 v151, v2, s27, v4 bitop3:0xde
	v_or_b32_e32 v2, s26, v3
	v_lshlrev_b32_e32 v3, 14, v15
	v_and_b32_e32 v3, 0xffff8000, v3
	v_lshl_add_u32 v3, v14, 11, v3
	v_and_b32_e32 v4, 1, v15
	v_lshl_or_b32 v3, v4, 6, v3
	v_lshl_add_u32 v140, v16, 1, v3
	v_lshlrev_b32_e32 v3, 14, v11
	v_and_b32_e32 v3, 0xffff8000, v3
	s_waitcnt vmcnt(6)
	v_lshl_add_u32 v3, v12, 11, v3
	v_and_b32_e32 v4, 1, v11
	s_sext_i32_i16 s47, s16
	s_cselect_b64 s[16:17], -1, 0
	v_lshl_or_b32 v3, v4, 6, v3
	s_add_i32 s66, 0, 0x10000
	s_add_i32 s67, 0, 0x14000
	v_or_b32_e32 v152, 16, v150
	v_or_b32_e32 v153, 32, v150
	v_or_b32_e32 v154, 48, v150
	s_ashr_i32 s64, s38, 31
	s_mov_b32 s65, s38
	v_mov_b32_e32 v141, v139
	v_lshl_add_u32 v142, v13, 1, v3
	v_mov_b32_e32 v143, v139
	v_mov_b64_e32 v[144:145], 0xb00
	v_mov_b64_e32 v[146:147], 0xaff
	v_add_u32_e32 v155, s66, v151
	v_add_u32_e32 v156, s67, v151
	v_add_u32_e32 v157, 0, v5
	v_mov_b32_e32 v158, 0x358637bd
	s_movk_i32 s68, 0x1600
	v_lshlrev_b32_e32 v138, 1, v2
	s_add_u32 s98, s48, 0x40080
	s_addc_u32 s99, s49, 0
	v_lshl_add_u64 v[148:149], s[98:99], 0, v[140:141]
	s_add_i32 m0, s57, 0xc000
	s_nop 0
	global_load_lds_dwordx4 v[148:149], off
	v_lshl_add_u64 v[148:149], s[98:99], 0, v[142:143]
	s_add_i32 m0, s57, 0xe000
	s_nop 0
	global_load_lds_dwordx4 v[148:149], off
	s_waitcnt vmcnt(0)
	s_barrier
	s_branch .LBB0_1127

.LBB0_1133:
	v_pk_mul_f32 v[128:129], v[120:121], v[128:129]
	v_pk_mul_f32 v[126:127], v[118:119], v[126:127]
	v_pk_mul_f32 v[124:125], v[116:117], v[124:125]
	v_pk_mul_f32 v[160:161], v[114:115], v[122:123]
	v_add_u32_e32 v162, s25, v152
	s_lshl_b32 s46, s47, 7
	v_mov_b64_e32 v[122:123], s[10:11]
	s_ashr_i32 s47, s46, 31
	v_mad_i64_i32 v[164:165], s[48:49], v148, s68, v[122:123]
	s_lshl_b64 s[46:47], s[46:47], 1
	v_lshl_add_u64 v[164:165], v[164:165], 0, s[46:47]
	v_lshl_add_u64 v[164:165], v[164:165], 0, v[138:139]
	v_pk_mul_f32 v[112:113], v[108:109], v[112:113]
	v_pk_mul_f32 v[110:111], v[106:107], v[110:111]
	v_pk_mul_f32 v[104:105], v[100:101], v[104:105]
	v_pk_mul_f32 v[102:103], v[98:99], v[102:103]
	v_pk_mul_f32 v[96:97], v[92:93], v[96:97]
	v_pk_mul_f32 v[94:95], v[90:91], v[94:95]
	v_pk_mul_f32 v[88:89], v[84:85], v[88:89]
	v_pk_mul_f32 v[86:87], v[82:83], v[86:87]
	v_pk_mul_f32 v[80:81], v[76:77], v[80:81]
	v_pk_mul_f32 v[78:79], v[74:75], v[78:79]
	v_pk_mul_f32 v[72:73], v[68:69], v[72:73]
	v_pk_mul_f32 v[70:71], v[66:67], v[70:71]
	v_pk_mul_f32 v[64:65], v[60:61], v[64:65]
	v_pk_mul_f32 v[62:63], v[58:59], v[62:63]
	v_pk_mul_f32 v[56:57], v[52:53], v[56:57]
	v_pk_mul_f32 v[54:55], v[50:51], v[54:55]
	v_pk_mul_f32 v[48:49], v[44:45], v[48:49]
	v_pk_mul_f32 v[46:47], v[42:43], v[46:47]
	v_pk_mul_f32 v[40:41], v[36:37], v[40:41]
	v_pk_mul_f32 v[38:39], v[34:35], v[38:39]
	v_pk_mul_f32 v[32:33], v[28:29], v[32:33]
	v_pk_mul_f32 v[30:31], v[26:27], v[30:31]
	v_pk_mul_f32 v[24:25], v[20:21], v[24:25]
	v_pk_mul_f32 v[22:23], v[18:19], v[22:23]
	v_pk_mul_f32 v[16:17], v[12:13], v[16:17]
	v_pk_mul_f32 v[14:15], v[10:11], v[14:15]
	v_pk_mul_f32 v[4:5], v[8:9], v[4:5]
	v_pk_mul_f32 v[2:3], v[6:7], v[2:3]
	s_andn2_b64 vcc, exec, s[4:5]
	s_waitcnt vmcnt(0)
	v_fmamk_f32 v149, v149, 0x3a800000, v158
	v_rsq_f32_e32 v149, v149
	s_nop 0
	v_mul_f32_e32 v168, 0xbfb8aa3b, v149
	v_pk_mul_f32 v[120:121], v[120:121], v[168:169] op_sel_hi:[1,0]
	v_pk_mul_f32 v[118:119], v[118:119], v[168:169] op_sel_hi:[1,0]
	v_pk_mul_f32 v[116:117], v[116:117], v[168:169] op_sel_hi:[1,0]
	v_pk_mul_f32 v[114:115], v[114:115], v[168:169] op_sel_hi:[1,0]
	v_exp_f32_e32 v118, v118
	v_exp_f32_e32 v119, v119
	v_exp_f32_e32 v120, v120
	v_exp_f32_e32 v121, v121
	v_exp_f32_e32 v114, v114
	v_exp_f32_e32 v115, v115
	v_exp_f32_e32 v116, v116
	v_exp_f32_e32 v117, v117
	v_mul_f32_e32 v170, v149, v149
	v_add_f32_e32 v118, 1.0, v118
	v_add_f32_e32 v119, 1.0, v119
	v_add_f32_e32 v120, 1.0, v120
	v_add_f32_e32 v121, 1.0, v121
	v_add_f32_e32 v149, 1.0, v114
	v_add_f32_e32 v159, 1.0, v115
	v_add_f32_e32 v163, 1.0, v116
	v_add_f32_e32 v168, 1.0, v117
	v_rcp_f32_e32 v114, v118
	v_rcp_f32_e32 v115, v119
	v_rcp_f32_e32 v116, v120
	v_rcp_f32_e32 v117, v121
	v_rcp_f32_e32 v118, v149
	v_rcp_f32_e32 v119, v159
	v_rcp_f32_e32 v120, v163
	v_rcp_f32_e32 v121, v168
	v_pk_mul_f32 v[114:115], v[170:171], v[114:115] op_sel_hi:[0,1]
	v_pk_mul_f32 v[116:117], v[170:171], v[116:117] op_sel_hi:[0,1]
	v_pk_mul_f32 v[118:119], v[170:171], v[118:119] op_sel_hi:[0,1]
	v_pk_mul_f32 v[120:121], v[170:171], v[120:121] op_sel_hi:[0,1]
	v_pk_mul_f32 v[116:117], v[128:129], v[116:117]
	v_pk_mul_f32 v[114:115], v[126:127], v[114:115]
	v_pk_mul_f32 v[120:121], v[124:125], v[120:121]
	v_pk_mul_f32 v[118:119], v[160:161], v[118:119]
	v_cvt_pk_bf16_f32 v114, v114, v115
	v_cvt_pk_bf16_f32 v115, v116, v117
	v_cvt_pk_bf16_f32 v116, v118, v119
	v_cvt_pk_bf16_f32 v117, v120, v121
	global_store_dwordx4 v[164:165], v[114:117], off
	v_fmamk_f32 v118, v232, 0x3a800000, v158
	v_rsq_f32_e32 v121, v118
	v_add_u32_e32 v114, s25, v153
	v_mul_f32_e32 v120, 0xbfb8aa3b, v121
	v_pk_mul_f32 v[108:109], v[108:109], v[120:121] op_sel_hi:[1,0]
	v_pk_mul_f32 v[106:107], v[106:107], v[120:121] op_sel_hi:[1,0]
	v_pk_mul_f32 v[100:101], v[100:101], v[120:121] op_sel_hi:[1,0]
	v_pk_mul_f32 v[98:99], v[98:99], v[120:121] op_sel_hi:[1,0]
	v_exp_f32_e32 v106, v106
	v_exp_f32_e32 v107, v107
	v_exp_f32_e32 v108, v108
	v_exp_f32_e32 v109, v109
	v_exp_f32_e32 v98, v98
	v_exp_f32_e32 v99, v99
	v_exp_f32_e32 v100, v100
	v_exp_f32_e32 v101, v101
	v_mul_f32_e32 v124, v121, v121
	v_add_f32_e32 v106, 1.0, v106
	v_add_f32_e32 v107, 1.0, v107
	v_add_f32_e32 v108, 1.0, v108
	v_add_f32_e32 v109, 1.0, v109
	v_add_f32_e32 v115, 1.0, v98
	v_add_f32_e32 v120, 1.0, v99
	v_add_f32_e32 v121, 1.0, v100
	v_add_f32_e32 v125, 1.0, v101
	v_rcp_f32_e32 v98, v106
	v_rcp_f32_e32 v99, v107
	v_rcp_f32_e32 v100, v108
	v_rcp_f32_e32 v101, v109
	v_rcp_f32_e32 v106, v115
	v_rcp_f32_e32 v107, v120
	v_rcp_f32_e32 v108, v121
	v_rcp_f32_e32 v109, v125
	v_mad_i64_i32 v[116:117], s[48:49], v162, s68, v[122:123]
	v_pk_mul_f32 v[98:99], v[124:125], v[98:99] op_sel_hi:[0,1]
	v_pk_mul_f32 v[100:101], v[124:125], v[100:101] op_sel_hi:[0,1]
	v_pk_mul_f32 v[106:107], v[124:125], v[106:107] op_sel_hi:[0,1]
	v_pk_mul_f32 v[108:109], v[124:125], v[108:109] op_sel_hi:[0,1]
	v_lshl_add_u64 v[116:117], v[116:117], 0, s[46:47]
	v_pk_mul_f32 v[100:101], v[112:113], v[100:101]
	v_pk_mul_f32 v[98:99], v[110:111], v[98:99]
	v_pk_mul_f32 v[104:105], v[104:105], v[108:109]
	v_pk_mul_f32 v[102:103], v[102:103], v[106:107]
	v_lshl_add_u64 v[116:117], v[116:117], 0, v[138:139]
	v_cvt_pk_bf16_f32 v98, v98, v99
	v_cvt_pk_bf16_f32 v99, v100, v101
	v_cvt_pk_bf16_f32 v100, v102, v103
	v_cvt_pk_bf16_f32 v101, v104, v105
	global_store_dwordx4 v[116:117], v[98:101], off
	v_fmamk_f32 v102, v233, 0x3a800000, v158
	v_rsq_f32_e32 v105, v102
	v_add_u32_e32 v98, s25, v154
	v_mul_f32_e32 v104, 0xbfb8aa3b, v105
	v_pk_mul_f32 v[92:93], v[92:93], v[104:105] op_sel_hi:[1,0]
	v_pk_mul_f32 v[90:91], v[90:91], v[104:105] op_sel_hi:[1,0]
	v_pk_mul_f32 v[84:85], v[84:85], v[104:105] op_sel_hi:[1,0]
	v_pk_mul_f32 v[82:83], v[82:83], v[104:105] op_sel_hi:[1,0]
	v_exp_f32_e32 v90, v90
	v_exp_f32_e32 v91, v91
	v_exp_f32_e32 v92, v92
	v_exp_f32_e32 v93, v93
	v_exp_f32_e32 v82, v82
	v_exp_f32_e32 v83, v83
	v_exp_f32_e32 v84, v84
	v_exp_f32_e32 v85, v85
	v_mul_f32_e32 v106, v105, v105
	v_add_f32_e32 v90, 1.0, v90
	v_add_f32_e32 v91, 1.0, v91
	v_add_f32_e32 v92, 1.0, v92
	v_add_f32_e32 v93, 1.0, v93
	v_add_f32_e32 v99, 1.0, v82
	v_add_f32_e32 v104, 1.0, v83
	v_add_f32_e32 v105, 1.0, v84
	v_add_f32_e32 v107, 1.0, v85
	v_rcp_f32_e32 v82, v90
	v_rcp_f32_e32 v83, v91
	v_rcp_f32_e32 v84, v92
	v_rcp_f32_e32 v85, v93
	v_rcp_f32_e32 v90, v99
	v_rcp_f32_e32 v91, v104
	v_rcp_f32_e32 v92, v105
	v_rcp_f32_e32 v93, v107
	v_mad_i64_i32 v[100:101], s[48:49], v114, s68, v[122:123]
	v_pk_mul_f32 v[82:83], v[106:107], v[82:83] op_sel_hi:[0,1]
	v_pk_mul_f32 v[84:85], v[106:107], v[84:85] op_sel_hi:[0,1]
	v_pk_mul_f32 v[90:91], v[106:107], v[90:91] op_sel_hi:[0,1]
	v_pk_mul_f32 v[92:93], v[106:107], v[92:93] op_sel_hi:[0,1]
	v_lshl_add_u64 v[100:101], v[100:101], 0, s[46:47]
	v_pk_mul_f32 v[84:85], v[96:97], v[84:85]
	v_pk_mul_f32 v[82:83], v[94:95], v[82:83]
	v_pk_mul_f32 v[88:89], v[88:89], v[92:93]
	v_pk_mul_f32 v[86:87], v[86:87], v[90:91]
	v_lshl_add_u64 v[100:101], v[100:101], 0, v[138:139]
	v_cvt_pk_bf16_f32 v82, v82, v83
	v_cvt_pk_bf16_f32 v83, v84, v85
	v_cvt_pk_bf16_f32 v84, v86, v87
	v_cvt_pk_bf16_f32 v85, v88, v89
	global_store_dwordx4 v[100:101], v[82:85], off
	s_nop 0
	s_nop 0
	v_add_u32_e32 v84, 0x80, v148
	v_mad_i64_i32 v[82:83], s[48:49], v98, s68, v[122:123]
	v_lshl_add_u64 v[82:83], v[82:83], 0, s[46:47]
	v_lshl_add_u64 v[82:83], v[82:83], 0, v[138:139]
	v_fmamk_f32 v85, v234, 0x3a800000, v158
	v_rsq_f32_e32 v89, v85
	s_nop 0
	v_mul_f32_e32 v88, 0xbfb8aa3b, v89
	v_pk_mul_f32 v[76:77], v[76:77], v[88:89] op_sel_hi:[1,0]
	v_pk_mul_f32 v[74:75], v[74:75], v[88:89] op_sel_hi:[1,0]
	v_pk_mul_f32 v[68:69], v[68:69], v[88:89] op_sel_hi:[1,0]
	v_pk_mul_f32 v[66:67], v[66:67], v[88:89] op_sel_hi:[1,0]
	v_exp_f32_e32 v74, v74
	v_exp_f32_e32 v75, v75
	v_exp_f32_e32 v76, v76
	v_exp_f32_e32 v77, v77
	v_exp_f32_e32 v66, v66
	v_exp_f32_e32 v67, v67
	v_exp_f32_e32 v68, v68
	v_exp_f32_e32 v69, v69
	v_mul_f32_e32 v90, v89, v89
	v_add_f32_e32 v74, 1.0, v74
	v_add_f32_e32 v75, 1.0, v75
	v_add_f32_e32 v76, 1.0, v76
	v_add_f32_e32 v77, 1.0, v77
	v_add_f32_e32 v85, 1.0, v66
	v_add_f32_e32 v88, 1.0, v67
	v_add_f32_e32 v89, 1.0, v68
	v_add_f32_e32 v91, 1.0, v69
	v_rcp_f32_e32 v66, v74
	v_rcp_f32_e32 v67, v75
	v_rcp_f32_e32 v68, v76
	v_rcp_f32_e32 v69, v77
	v_rcp_f32_e32 v74, v85
	v_rcp_f32_e32 v75, v88
	v_rcp_f32_e32 v76, v89
	v_rcp_f32_e32 v77, v91
	v_pk_mul_f32 v[66:67], v[90:91], v[66:67] op_sel_hi:[0,1]
	v_pk_mul_f32 v[68:69], v[90:91], v[68:69] op_sel_hi:[0,1]
	v_pk_mul_f32 v[74:75], v[90:91], v[74:75] op_sel_hi:[0,1]
	v_pk_mul_f32 v[76:77], v[90:91], v[76:77] op_sel_hi:[0,1]
	v_pk_mul_f32 v[68:69], v[80:81], v[68:69]
	v_pk_mul_f32 v[66:67], v[78:79], v[66:67]
	v_pk_mul_f32 v[72:73], v[72:73], v[76:77]
	v_pk_mul_f32 v[70:71], v[70:71], v[74:75]
	v_cvt_pk_bf16_f32 v66, v66, v67
	v_cvt_pk_bf16_f32 v67, v68, v69
	v_cvt_pk_bf16_f32 v68, v70, v71
	v_cvt_pk_bf16_f32 v69, v72, v73
	global_store_dwordx4 v[82:83], v[66:69], off
	v_fmamk_f32 v70, v235, 0x3a800000, v158
	v_rsq_f32_e32 v73, v70
	v_add_u32_e32 v66, 0x90, v148
	v_mul_f32_e32 v72, 0xbfb8aa3b, v73
	v_pk_mul_f32 v[60:61], v[60:61], v[72:73] op_sel_hi:[1,0]
	v_pk_mul_f32 v[58:59], v[58:59], v[72:73] op_sel_hi:[1,0]
	v_pk_mul_f32 v[52:53], v[52:53], v[72:73] op_sel_hi:[1,0]
	v_pk_mul_f32 v[50:51], v[50:51], v[72:73] op_sel_hi:[1,0]
	v_exp_f32_e32 v58, v58
	v_exp_f32_e32 v59, v59
	v_exp_f32_e32 v60, v60
	v_exp_f32_e32 v61, v61
	v_exp_f32_e32 v50, v50
	v_exp_f32_e32 v51, v51
	v_exp_f32_e32 v52, v52
	v_exp_f32_e32 v53, v53
	v_mul_f32_e32 v74, v73, v73
	v_add_f32_e32 v58, 1.0, v58
	v_add_f32_e32 v59, 1.0, v59
	v_add_f32_e32 v60, 1.0, v60
	v_add_f32_e32 v61, 1.0, v61
	v_add_f32_e32 v67, 1.0, v50
	v_add_f32_e32 v72, 1.0, v51
	v_add_f32_e32 v73, 1.0, v52
	v_add_f32_e32 v75, 1.0, v53
	v_rcp_f32_e32 v50, v58
	v_rcp_f32_e32 v51, v59
	v_rcp_f32_e32 v52, v60
	v_rcp_f32_e32 v53, v61
	v_rcp_f32_e32 v58, v67
	v_rcp_f32_e32 v59, v72
	v_rcp_f32_e32 v60, v73
	v_rcp_f32_e32 v61, v75
	v_mad_i64_i32 v[68:69], s[48:49], v84, s68, v[122:123]
	v_pk_mul_f32 v[50:51], v[74:75], v[50:51] op_sel_hi:[0,1]
	v_pk_mul_f32 v[52:53], v[74:75], v[52:53] op_sel_hi:[0,1]
	v_pk_mul_f32 v[58:59], v[74:75], v[58:59] op_sel_hi:[0,1]
	v_pk_mul_f32 v[60:61], v[74:75], v[60:61] op_sel_hi:[0,1]
	v_lshl_add_u64 v[68:69], v[68:69], 0, s[46:47]
	v_pk_mul_f32 v[52:53], v[64:65], v[52:53]
	v_pk_mul_f32 v[50:51], v[62:63], v[50:51]
	v_pk_mul_f32 v[56:57], v[56:57], v[60:61]
	v_pk_mul_f32 v[54:55], v[54:55], v[58:59]
	v_lshl_add_u64 v[68:69], v[68:69], 0, v[138:139]
	v_cvt_pk_bf16_f32 v50, v50, v51
	v_cvt_pk_bf16_f32 v51, v52, v53
	v_cvt_pk_bf16_f32 v52, v54, v55
	v_cvt_pk_bf16_f32 v53, v56, v57
	global_store_dwordx4 v[68:69], v[50:53], off
	v_fmamk_f32 v54, v236, 0x3a800000, v158
	v_rsq_f32_e32 v57, v54
	v_add_u32_e32 v50, 0xa0, v148
	v_mul_f32_e32 v56, 0xbfb8aa3b, v57
	v_pk_mul_f32 v[44:45], v[44:45], v[56:57] op_sel_hi:[1,0]
	v_pk_mul_f32 v[42:43], v[42:43], v[56:57] op_sel_hi:[1,0]
	v_pk_mul_f32 v[36:37], v[36:37], v[56:57] op_sel_hi:[1,0]
	v_pk_mul_f32 v[34:35], v[34:35], v[56:57] op_sel_hi:[1,0]
	v_exp_f32_e32 v42, v42
	v_exp_f32_e32 v43, v43
	v_exp_f32_e32 v44, v44
	v_exp_f32_e32 v45, v45
	v_exp_f32_e32 v34, v34
	v_exp_f32_e32 v35, v35
	v_exp_f32_e32 v36, v36
	v_exp_f32_e32 v37, v37
	v_mul_f32_e32 v58, v57, v57
	v_add_f32_e32 v42, 1.0, v42
	v_add_f32_e32 v43, 1.0, v43
	v_add_f32_e32 v44, 1.0, v44
	v_add_f32_e32 v45, 1.0, v45
	v_add_f32_e32 v51, 1.0, v34
	v_add_f32_e32 v56, 1.0, v35
	v_add_f32_e32 v57, 1.0, v36
	v_add_f32_e32 v59, 1.0, v37
	v_rcp_f32_e32 v34, v42
	v_rcp_f32_e32 v35, v43
	v_rcp_f32_e32 v36, v44
	v_rcp_f32_e32 v37, v45
	v_rcp_f32_e32 v42, v51
	v_rcp_f32_e32 v43, v56
	v_rcp_f32_e32 v44, v57
	v_rcp_f32_e32 v45, v59
	v_mad_i64_i32 v[52:53], s[48:49], v66, s68, v[122:123]
	v_pk_mul_f32 v[34:35], v[58:59], v[34:35] op_sel_hi:[0,1]
	v_pk_mul_f32 v[36:37], v[58:59], v[36:37] op_sel_hi:[0,1]
	v_pk_mul_f32 v[42:43], v[58:59], v[42:43] op_sel_hi:[0,1]
	v_pk_mul_f32 v[44:45], v[58:59], v[44:45] op_sel_hi:[0,1]
	v_lshl_add_u64 v[52:53], v[52:53], 0, s[46:47]
	v_pk_mul_f32 v[36:37], v[48:49], v[36:37]
	v_pk_mul_f32 v[34:35], v[46:47], v[34:35]
	v_pk_mul_f32 v[40:41], v[40:41], v[44:45]
	v_pk_mul_f32 v[38:39], v[38:39], v[42:43]
	v_lshl_add_u64 v[52:53], v[52:53], 0, v[138:139]
	v_cvt_pk_bf16_f32 v34, v34, v35
	v_cvt_pk_bf16_f32 v35, v36, v37
	v_cvt_pk_bf16_f32 v36, v38, v39
	v_cvt_pk_bf16_f32 v37, v40, v41
	global_store_dwordx4 v[52:53], v[34:37], off
	v_fmamk_f32 v38, v237, 0x3a800000, v158
	v_rsq_f32_e32 v41, v38
	v_add_u32_e32 v34, 0xb0, v148
	v_mul_f32_e32 v40, 0xbfb8aa3b, v41
	v_pk_mul_f32 v[28:29], v[28:29], v[40:41] op_sel_hi:[1,0]
	v_pk_mul_f32 v[26:27], v[26:27], v[40:41] op_sel_hi:[1,0]
	v_pk_mul_f32 v[20:21], v[20:21], v[40:41] op_sel_hi:[1,0]
	v_pk_mul_f32 v[18:19], v[18:19], v[40:41] op_sel_hi:[1,0]
	v_exp_f32_e32 v26, v26
	v_exp_f32_e32 v27, v27
	v_exp_f32_e32 v28, v28
	v_exp_f32_e32 v29, v29
	v_exp_f32_e32 v18, v18
	v_exp_f32_e32 v19, v19
	v_exp_f32_e32 v20, v20
	v_exp_f32_e32 v21, v21
	v_mul_f32_e32 v42, v41, v41
	v_add_f32_e32 v26, 1.0, v26
	v_add_f32_e32 v27, 1.0, v27
	v_add_f32_e32 v28, 1.0, v28
	v_add_f32_e32 v29, 1.0, v29
	v_add_f32_e32 v35, 1.0, v18
	v_add_f32_e32 v40, 1.0, v19
	v_add_f32_e32 v41, 1.0, v20
	v_add_f32_e32 v43, 1.0, v21
	v_rcp_f32_e32 v18, v26
	v_rcp_f32_e32 v19, v27
	v_rcp_f32_e32 v20, v28
	v_rcp_f32_e32 v21, v29
	v_rcp_f32_e32 v26, v35
	v_rcp_f32_e32 v27, v40
	v_rcp_f32_e32 v28, v41
	v_rcp_f32_e32 v29, v43
	v_mad_i64_i32 v[36:37], s[48:49], v50, s68, v[122:123]
	v_pk_mul_f32 v[18:19], v[42:43], v[18:19] op_sel_hi:[0,1]
	v_pk_mul_f32 v[20:21], v[42:43], v[20:21] op_sel_hi:[0,1]
	v_pk_mul_f32 v[26:27], v[42:43], v[26:27] op_sel_hi:[0,1]
	v_pk_mul_f32 v[28:29], v[42:43], v[28:29] op_sel_hi:[0,1]
	v_lshl_add_u64 v[36:37], v[36:37], 0, s[46:47]
	v_pk_mul_f32 v[20:21], v[32:33], v[20:21]
	v_pk_mul_f32 v[18:19], v[30:31], v[18:19]
	v_pk_mul_f32 v[24:25], v[24:25], v[28:29]
	v_pk_mul_f32 v[22:23], v[22:23], v[26:27]
	v_lshl_add_u64 v[36:37], v[36:37], 0, v[138:139]
	v_cvt_pk_bf16_f32 v18, v18, v19
	v_cvt_pk_bf16_f32 v19, v20, v21
	v_cvt_pk_bf16_f32 v20, v22, v23
	v_cvt_pk_bf16_f32 v21, v24, v25
	global_store_dwordx4 v[36:37], v[18:21], off
	s_nop 0
	s_nop 0
	v_fmamk_f32 v18, v238, 0x3a800000, v158
	v_rsq_f32_e32 v21, v18
	v_mad_i64_i32 v[18:19], s[4:5], v34, s68, v[122:123]
	v_lshl_add_u64 v[18:19], v[18:19], 0, s[46:47]
	v_mul_f32_e32 v20, 0xbfb8aa3b, v21
	v_pk_mul_f32 v[12:13], v[12:13], v[20:21] op_sel_hi:[1,0]
	v_pk_mul_f32 v[10:11], v[10:11], v[20:21] op_sel_hi:[1,0]
	v_pk_mul_f32 v[8:9], v[8:9], v[20:21] op_sel_hi:[1,0]
	v_pk_mul_f32 v[6:7], v[6:7], v[20:21] op_sel_hi:[1,0]
	v_exp_f32_e32 v10, v10
	v_exp_f32_e32 v11, v11
	v_exp_f32_e32 v12, v12
	v_exp_f32_e32 v13, v13
	v_exp_f32_e32 v6, v6
	v_exp_f32_e32 v7, v7
	v_exp_f32_e32 v8, v8
	v_exp_f32_e32 v9, v9
	v_mul_f32_e32 v22, v21, v21
	v_add_f32_e32 v10, 1.0, v10
	v_add_f32_e32 v11, 1.0, v11
	v_add_f32_e32 v12, 1.0, v12
	v_add_f32_e32 v13, 1.0, v13
	v_add_f32_e32 v20, 1.0, v6
	v_add_f32_e32 v21, 1.0, v7
	v_add_f32_e32 v23, 1.0, v8
	v_add_f32_e32 v24, 1.0, v9
	v_rcp_f32_e32 v6, v10
	v_rcp_f32_e32 v7, v11
	v_rcp_f32_e32 v8, v12
	v_rcp_f32_e32 v9, v13
	v_rcp_f32_e32 v10, v20
	v_rcp_f32_e32 v11, v21
	v_rcp_f32_e32 v12, v23
	v_rcp_f32_e32 v13, v24
	v_pk_mul_f32 v[6:7], v[22:23], v[6:7] op_sel_hi:[0,1]
	v_pk_mul_f32 v[8:9], v[22:23], v[8:9] op_sel_hi:[0,1]
	v_pk_mul_f32 v[10:11], v[22:23], v[10:11] op_sel_hi:[0,1]
	v_pk_mul_f32 v[12:13], v[22:23], v[12:13] op_sel_hi:[0,1]
	v_pk_mul_f32 v[8:9], v[16:17], v[8:9]
	v_pk_mul_f32 v[6:7], v[14:15], v[6:7]
	v_pk_mul_f32 v[12:13], v[4:5], v[12:13]
	v_pk_mul_f32 v[4:5], v[2:3], v[10:11]
	v_lshl_add_u64 v[18:19], v[18:19], 0, v[138:139]
	v_cvt_pk_bf16_f32 v2, v6, v7
	v_cvt_pk_bf16_f32 v3, v8, v9
	v_cvt_pk_bf16_f32 v4, v4, v5
	v_cvt_pk_bf16_f32 v5, v12, v13
	s_mov_b64 s[4:5], -1
	global_store_dwordx4 v[18:19], v[2:5], off
	s_cbranch_vccnz .LBB0_1126
	s_andn2_b64 vcc, exec, s[6:7]
	s_cbranch_vccnz .LBB0_1125
	s_branch .LBB0_1125

.LBB0_1804:
	s_waitcnt lgkmcnt(0)
	s_add_u32 s10, s10, 0xe0000
	s_addc_u32 s11, s11, 0
	s_add_u32 s12, s4, 0xa400000
	s_addc_u32 s13, s5, 0
	s_lshl_b32 s4, s14, 5
	s_mov_b64 s[14:15], 0x80
	s_and_b32 s26, s4, 0x60
	s_add_i32 m0, s57, 0x18000
	v_lshl_add_u64 v[8:9], v[8:9], 0, s[14:15]
	s_lshl_b32 s25, s24, 13
	s_lshl_b32 s27, s26, 7
	s_waitcnt vmcnt(2)
	global_load_lds_dwordx4 v[8:9], off
	v_lshl_add_u64 v[6:7], v[6:7], 0, s[14:15]
	s_add_i32 m0, s57, 0x1a000
	s_add_i32 s62, s57, 0x8000
	s_add_i32 s63, s57, 0xa000
	global_load_lds_dwordx4 v[6:7], off
	v_lshl_add_u64 v[2:3], v[2:3], 0, s[14:15]
	s_mov_b32 m0, s62
	s_add_u32 s4, s50, 0x40080
	global_load_lds_dwordx4 v[2:3], off
	v_lshl_add_u64 v[2:3], v[4:5], 0, s[14:15]
	s_mov_b32 m0, s63
	s_addc_u32 s5, s51, 0
	global_load_lds_dwordx4 v[2:3], off
	s_add_i32 m0, s57, 0x1c000
	v_lshl_add_u64 v[2:3], s[4:5], 0, v[134:135]
	global_load_lds_dwordx4 v[2:3], off
	v_lshl_add_u64 v[2:3], s[4:5], 0, v[130:131]
	s_add_i32 m0, s57, 0x1e000
	s_cmpk_lt_u32 s17, 0x100
	global_load_lds_dwordx4 v[2:3], off
	v_lshrrev_b32_e32 v3, 1, v10
	v_and_b32_e32 v3, 24, v3
	v_and_b32_e32 v2, 15, v10
	v_lshlrev_b32_e32 v4, 1, v3
	v_lshl_or_b32 v150, s24, 6, v2
	v_lshl_or_b32 v2, v2, 6, v4
	v_lshlrev_b32_e32 v4, 2, v10
	v_and_b32_e32 v4, 32, v4
	v_bitop3_b32 v5, v2, s25, v4 bitop3:0xde
	v_bitop3_b32 v151, v2, s27, v4 bitop3:0xde
	v_or_b32_e32 v2, s26, v3
	v_lshlrev_b32_e32 v3, 14, v15
	v_and_b32_e32 v3, 0xffff8000, v3
	v_lshl_add_u32 v3, v14, 11, v3
	v_and_b32_e32 v4, 1, v15
	v_lshl_or_b32 v3, v4, 6, v3
	v_lshl_add_u32 v140, v16, 1, v3
	v_lshlrev_b32_e32 v3, 14, v11
	v_and_b32_e32 v3, 0xffff8000, v3
	s_waitcnt vmcnt(6)
	v_lshl_add_u32 v3, v12, 11, v3
	v_and_b32_e32 v4, 1, v11
	s_sext_i32_i16 s47, s16
	s_cselect_b64 s[16:17], -1, 0
	v_lshl_or_b32 v3, v4, 6, v3
	s_add_i32 s66, 0, 0x10000
	s_add_i32 s67, 0, 0x14000
	v_or_b32_e32 v152, 16, v150
	v_or_b32_e32 v153, 32, v150
	v_or_b32_e32 v154, 48, v150
	s_ashr_i32 s64, s38, 31
	s_mov_b32 s65, s38
	v_mov_b32_e32 v141, v139
	v_lshl_add_u32 v142, v13, 1, v3
	v_mov_b32_e32 v143, v139
	v_mov_b64_e32 v[144:145], 0xb00
	v_mov_b64_e32 v[146:147], 0xaff
	v_add_u32_e32 v155, s66, v151
	v_add_u32_e32 v156, s67, v151
	v_add_u32_e32 v157, 0, v5
	v_mov_b32_e32 v158, 0x358637bd
	s_movk_i32 s68, 0x1600
	v_lshlrev_b32_e32 v138, 1, v2
	s_add_u32 s98, s48, 0x40080
	s_addc_u32 s99, s49, 0
	v_lshl_add_u64 v[148:149], s[98:99], 0, v[140:141]
	s_add_i32 m0, s57, 0xc000
	s_nop 0
	global_load_lds_dwordx4 v[148:149], off
	v_lshl_add_u64 v[148:149], s[98:99], 0, v[142:143]
	s_add_i32 m0, s57, 0xe000
	s_nop 0
	global_load_lds_dwordx4 v[148:149], off
	s_waitcnt vmcnt(0)
	s_barrier
	s_branch .LBB0_1807

	.amdhsa_kernel _Z8yoco_fwd4Args
		.amdhsa_group_segment_fixed_size 0
		.amdhsa_private_segment_fixed_size 0
		.amdhsa_kernarg_size 448
		.amdhsa_user_sgpr_count 2
		.amdhsa_user_sgpr_dispatch_ptr 0
		.amdhsa_user_sgpr_queue_ptr 0
		.amdhsa_user_sgpr_kernarg_segment_ptr 1
		.amdhsa_user_sgpr_dispatch_id 0
		.amdhsa_user_sgpr_kernarg_preload_length 0
		.amdhsa_user_sgpr_kernarg_preload_offset 0
		.amdhsa_user_sgpr_private_segment_size 0
		.amdhsa_uses_dynamic_stack 0
		.amdhsa_enable_private_segment 0
		.amdhsa_system_sgpr_workgroup_id_x 1
		.amdhsa_system_sgpr_workgroup_id_y 0
		.amdhsa_system_sgpr_workgroup_id_z 0
		.amdhsa_system_sgpr_workgroup_info 0
		.amdhsa_system_vgpr_workitem_id 2
		.amdhsa_next_free_vgpr 256
		.amdhsa_next_free_sgpr 100
		.amdhsa_accum_offset 256
		.amdhsa_reserve_vcc 1
		.amdhsa_float_round_mode_32 0
		.amdhsa_float_round_mode_16_64 0
		.amdhsa_float_denorm_mode_32 3
		.amdhsa_float_denorm_mode_16_64 3
		.amdhsa_dx10_clamp 1
		.amdhsa_ieee_mode 1
		.amdhsa_fp16_overflow 0
		.amdhsa_tg_split 0
		.amdhsa_exception_fp_ieee_invalid_op 0
		.amdhsa_exception_fp_denorm_src 0
		.amdhsa_exception_fp_ieee_div_zero 0
		.amdhsa_exception_fp_ieee_overflow 0
		.amdhsa_exception_fp_ieee_underflow 0
		.amdhsa_exception_fp_ieee_inexact 0
		.amdhsa_exception_int_div_zero 0
	.end_amdhsa_kernel

amdhsa.kernels:
  - .agpr_count:     0
    .args:
      - .offset:         0
        .size:           192
        .value_kind:     by_value
      - .offset:         192
        .size:           4
        .value_kind:     hidden_block_count_x
      - .offset:         196
        .size:           4
        .value_kind:     hidden_block_count_y
      - .offset:         200
        .size:           4
        .value_kind:     hidden_block_count_z
      - .offset:         204
        .size:           2
        .value_kind:     hidden_group_size_x
      - .offset:         206
        .size:           2
        .value_kind:     hidden_group_size_y
      - .offset:         208
        .size:           2
        .value_kind:     hidden_group_size_z
      - .offset:         210
        .size:           2
        .value_kind:     hidden_remainder_x
      - .offset:         212
        .size:           2
        .value_kind:     hidden_remainder_y
      - .offset:         214
        .size:           2
        .value_kind:     hidden_remainder_z
      - .offset:         232
        .size:           8
        .value_kind:     hidden_global_offset_x
      - .offset:         240
        .size:           8
        .value_kind:     hidden_global_offset_y
      - .offset:         248
        .size:           8
        .value_kind:     hidden_global_offset_z
      - .offset:         256
        .size:           2
        .value_kind:     hidden_grid_dims
      - .offset:         280
        .size:           8
        .value_kind:     hidden_multigrid_sync_arg
      - .offset:         312
        .size:           4
        .value_kind:     hidden_dynamic_lds_size
    .group_segment_fixed_size: 0
    .kernarg_segment_align: 8
    .kernarg_segment_size: 448
    .language:       OpenCL C
    .language_version:
      - 2
      - 0
    .max_flat_workgroup_size: 512
    .name:           _Z8yoco_fwd4Args
    .private_segment_fixed_size: 0
    .sgpr_count:     106
    .sgpr_spill_count: 0
    .symbol:         _Z8yoco_fwd4Args.kd
    .uniform_work_group_size: 1
    .uses_dynamic_stack: false
    .vgpr_count:     256
    .vgpr_spill_count: 0
    .wavefront_size: 64
